# hot K-loops: s_setprio toggles removed entirely (on top of the in-loop rec write-out)
# speedup vs baseline: 1.0458x; 1.0027x over previous
.LBB0_384:
	ds_read_b128 v[134:137], v199
	ds_read_b128 v[138:141], v200
	ds_read_b128 v[142:145], v201
	ds_read_b128 v[146:149], v202
	ds_read_b128 v[150:153], v203
	ds_read_b128 v[174:177], v204
	ds_read_b128 v[178:181], v205
	ds_read_b128 v[182:185], v206
	s_add_u32 s24, s4, vcc_lo
	s_addc_u32 s25, s5, vcc_hi
	s_add_u32 s24, s24, 0x100
	s_addc_u32 s25, s25, 0
	s_add_u32 s82, s39, vcc_lo
	s_addc_u32 s83, s67, vcc_hi
	s_cmpk_eq_i32 vcc_lo, 0x700
	s_cselect_b32 s87, s29, s83
	s_cselect_b32 s86, s38, s82
	s_cselect_b32 s83, s34, s25
	s_cselect_b32 s82, s35, s24
	v_lshl_add_u64 v[154:155], v[132:133], 0, vcc
	v_lshl_add_u64 v[250:251], v[154:155], 0, s[48:49]
	s_add_i32 m0, s79, 0x8000
	s_mov_b64 s[24:25], 0x20080
	ds_read_b128 v[218:221], v207
	ds_read_b128 v[222:225], v207 offset:2048
	ds_read_b128 v[226:229], v208
	ds_read_b128 v[230:233], v208 offset:2048
	ds_read_b128 v[234:237], v207 offset:4096
	ds_read_b128 v[238:241], v207 offset:6144
	ds_read_b128 v[242:245], v208 offset:4096
	ds_read_b128 v[246:249], v208 offset:6144
	global_load_lds_dwordx4 v[250:251], off
	v_lshl_add_u64 v[250:251], v[154:155], 0, s[24:25]
	s_add_i32 m0, s79, 0xa000
	s_mov_b64 s[24:25], 0x60080
	global_load_lds_dwordx4 v[250:251], off
	v_lshl_add_u64 v[250:251], v[154:155], 0, s[50:51]
	s_add_i32 m0, s79, 0xc000
	v_lshl_add_u64 v[154:155], v[154:155], 0, s[24:25]
	global_load_lds_dwordx4 v[250:251], off
	s_add_i32 m0, s79, 0xe000
	s_nop 0
	global_load_lds_dwordx4 v[154:155], off
	s_waitcnt vmcnt(8)
	s_waitcnt lgkmcnt(0)
	s_barrier
	v_mfma_f32_16x16x32_bf16 v[128:131], v[134:137], v[218:221], v[128:131]
	v_mfma_f32_16x16x32_bf16 v[124:127], v[142:145], v[218:221], v[124:127]
	v_mfma_f32_16x16x32_bf16 v[112:115], v[134:137], v[222:225], v[112:115]
	v_mfma_f32_16x16x32_bf16 v[108:111], v[142:145], v[222:225], v[108:111]
	v_mfma_f32_16x16x32_bf16 v[96:99], v[134:137], v[234:237], v[96:99]
	v_mfma_f32_16x16x32_bf16 v[92:95], v[142:145], v[234:237], v[92:95]
	v_mfma_f32_16x16x32_bf16 v[80:83], v[134:137], v[238:241], v[80:83]
	v_mfma_f32_16x16x32_bf16 v[76:79], v[142:145], v[238:241], v[76:79]
	v_mfma_f32_16x16x32_bf16 v[128:131], v[138:141], v[226:229], v[128:131]
	v_mfma_f32_16x16x32_bf16 v[124:127], v[146:149], v[226:229], v[124:127]
	v_mfma_f32_16x16x32_bf16 v[112:115], v[138:141], v[230:233], v[112:115]
	v_mfma_f32_16x16x32_bf16 v[108:111], v[146:149], v[230:233], v[108:111]
	v_mfma_f32_16x16x32_bf16 v[96:99], v[138:141], v[242:245], v[96:99]
	v_mfma_f32_16x16x32_bf16 v[92:95], v[146:149], v[242:245], v[92:95]
	v_mfma_f32_16x16x32_bf16 v[80:83], v[138:141], v[246:249], v[80:83]
	v_mfma_f32_16x16x32_bf16 v[76:79], v[146:149], v[246:249], v[76:79]
	v_mfma_f32_16x16x32_bf16 v[120:123], v[150:153], v[218:221], v[120:123]
	v_mfma_f32_16x16x32_bf16 v[116:119], v[178:181], v[218:221], v[116:119]
	v_mfma_f32_16x16x32_bf16 v[104:107], v[150:153], v[222:225], v[104:107]
	v_mfma_f32_16x16x32_bf16 v[100:103], v[178:181], v[222:225], v[100:103]
	v_mfma_f32_16x16x32_bf16 v[88:91], v[150:153], v[234:237], v[88:91]
	v_mfma_f32_16x16x32_bf16 v[84:87], v[178:181], v[234:237], v[84:87]
	v_mfma_f32_16x16x32_bf16 v[72:75], v[150:153], v[238:241], v[72:75]
	v_mfma_f32_16x16x32_bf16 v[68:71], v[178:181], v[238:241], v[68:71]
	v_mfma_f32_16x16x32_bf16 v[120:123], v[174:177], v[226:229], v[120:123]
	v_mfma_f32_16x16x32_bf16 v[116:119], v[182:185], v[226:229], v[116:119]
	v_mfma_f32_16x16x32_bf16 v[104:107], v[174:177], v[230:233], v[104:107]
	v_mfma_f32_16x16x32_bf16 v[100:103], v[182:185], v[230:233], v[100:103]
	v_mfma_f32_16x16x32_bf16 v[88:91], v[174:177], v[242:245], v[88:91]
	v_mfma_f32_16x16x32_bf16 v[84:87], v[182:185], v[242:245], v[84:87]
	v_mfma_f32_16x16x32_bf16 v[72:75], v[174:177], v[246:249], v[72:75]
	v_mfma_f32_16x16x32_bf16 v[68:71], v[182:185], v[246:249], v[68:71]
	s_barrier
	s_add_i32 s24, s1, s77
	v_lshl_add_u64 v[154:155], s[86:87], 0, v[158:159]
	s_mov_b32 m0, s24
	ds_read_b128 v[218:221], v207 offset:16384
	ds_read_b128 v[222:225], v207 offset:18432
	ds_read_b128 v[226:229], v208 offset:16384
	ds_read_b128 v[230:233], v208 offset:18432
	ds_read_b128 v[234:237], v207 offset:20480
	ds_read_b128 v[238:241], v207 offset:22528
	ds_read_b128 v[242:245], v208 offset:20480
	ds_read_b128 v[246:249], v208 offset:22528
	global_load_lds_dwordx4 v[154:155], off
	v_lshl_add_u64 v[250:251], v[154:155], 0, s[14:15]
	s_add_i32 m0, s24, 0x2000
	s_add_i32 s24, s12, s77
	global_load_lds_dwordx4 v[250:251], off
	v_lshl_add_u64 v[250:251], v[154:155], 0, s[16:17]
	s_mov_b32 m0, s24
	s_nop 0
	global_load_lds_dwordx4 v[250:251], off
	v_lshl_add_u64 v[250:251], v[154:155], 0, s[18:19]
	s_add_i32 m0, s24, 0x2000
	s_nop 0
	global_load_lds_dwordx4 v[250:251], off
	s_waitcnt vmcnt(4)
	s_waitcnt lgkmcnt(0)
	s_barrier
	v_mfma_f32_16x16x32_bf16 v[64:67], v[134:137], v[218:221], v[64:67]
	v_mfma_f32_16x16x32_bf16 v[60:63], v[142:145], v[218:221], v[60:63]
	v_mfma_f32_16x16x32_bf16 v[48:51], v[134:137], v[222:225], v[48:51]
	v_mfma_f32_16x16x32_bf16 v[44:47], v[142:145], v[222:225], v[44:47]
	v_mfma_f32_16x16x32_bf16 v[32:35], v[134:137], v[234:237], v[32:35]
	v_mfma_f32_16x16x32_bf16 v[28:31], v[142:145], v[234:237], v[28:31]
	v_mfma_f32_16x16x32_bf16 v[16:19], v[134:137], v[238:241], v[16:19]
	v_mfma_f32_16x16x32_bf16 v[12:15], v[142:145], v[238:241], v[12:15]
	v_mfma_f32_16x16x32_bf16 v[64:67], v[138:141], v[226:229], v[64:67]
	v_mfma_f32_16x16x32_bf16 v[60:63], v[146:149], v[226:229], v[60:63]
	v_mfma_f32_16x16x32_bf16 v[48:51], v[138:141], v[230:233], v[48:51]
	v_mfma_f32_16x16x32_bf16 v[44:47], v[146:149], v[230:233], v[44:47]
	v_mfma_f32_16x16x32_bf16 v[32:35], v[138:141], v[242:245], v[32:35]
	v_mfma_f32_16x16x32_bf16 v[28:31], v[146:149], v[242:245], v[28:31]
	v_mfma_f32_16x16x32_bf16 v[16:19], v[138:141], v[246:249], v[16:19]
	v_mfma_f32_16x16x32_bf16 v[12:15], v[146:149], v[246:249], v[12:15]
	v_mfma_f32_16x16x32_bf16 v[56:59], v[150:153], v[218:221], v[56:59]
	v_mfma_f32_16x16x32_bf16 v[52:55], v[178:181], v[218:221], v[52:55]
	v_mfma_f32_16x16x32_bf16 v[40:43], v[150:153], v[222:225], v[40:43]
	v_mfma_f32_16x16x32_bf16 v[36:39], v[178:181], v[222:225], v[36:39]
	v_mfma_f32_16x16x32_bf16 v[24:27], v[150:153], v[234:237], v[24:27]
	v_mfma_f32_16x16x32_bf16 v[20:23], v[178:181], v[234:237], v[20:23]
	v_mfma_f32_16x16x32_bf16 v[8:11], v[150:153], v[238:241], v[8:11]
	v_mfma_f32_16x16x32_bf16 v[4:7], v[178:181], v[238:241], v[4:7]
	v_mfma_f32_16x16x32_bf16 v[56:59], v[174:177], v[226:229], v[56:59]
	v_mfma_f32_16x16x32_bf16 v[52:55], v[182:185], v[226:229], v[52:55]
	v_mfma_f32_16x16x32_bf16 v[40:43], v[174:177], v[230:233], v[40:43]
	v_mfma_f32_16x16x32_bf16 v[36:39], v[182:185], v[230:233], v[36:39]
	v_mfma_f32_16x16x32_bf16 v[24:27], v[174:177], v[242:245], v[24:27]
	v_mfma_f32_16x16x32_bf16 v[20:23], v[182:185], v[242:245], v[20:23]
	v_mfma_f32_16x16x32_bf16 v[8:11], v[174:177], v[246:249], v[8:11]
	v_mfma_f32_16x16x32_bf16 v[4:7], v[182:185], v[246:249], v[4:7]
	s_barrier
	ds_read_b128 v[134:137], v213
	ds_read_b128 v[138:141], v214
	ds_read_b128 v[142:145], v209
	ds_read_b128 v[146:149], v210
	ds_read_b128 v[150:153], v215
	ds_read_b128 v[174:177], v216
	ds_read_b128 v[178:181], v211
	ds_read_b128 v[182:185], v212
	s_mov_b32 m0, s79
	v_lshl_add_u64 v[250:251], s[82:83], 0, v[0:1]
	ds_read_b128 v[218:221], v207 offset:32768
	ds_read_b128 v[222:225], v207 offset:34816
	ds_read_b128 v[226:229], v208 offset:32768
	ds_read_b128 v[230:233], v208 offset:34816
	ds_read_b128 v[234:237], v207 offset:36864
	ds_read_b128 v[238:241], v207 offset:38912
	ds_read_b128 v[242:245], v208 offset:36864
	ds_read_b128 v[246:249], v208 offset:38912
	global_load_lds_dwordx4 v[250:251], off
	v_lshl_add_u64 v[252:253], v[250:251], 0, s[20:21]
	s_mov_b32 m0, s81
	s_nop 0
	global_load_lds_dwordx4 v[252:253], off
	v_lshl_add_u64 v[252:253], v[250:251], 0, s[14:15]
	s_mov_b32 m0, s97
	v_lshl_add_u64 v[250:251], v[250:251], 0, s[22:23]
	global_load_lds_dwordx4 v[252:253], off
	s_mov_b32 m0, s64
	s_nop 0
	global_load_lds_dwordx4 v[250:251], off
	s_waitcnt vmcnt(8)
	s_waitcnt lgkmcnt(0)
	s_barrier
	v_mfma_f32_16x16x32_bf16 v[128:131], v[134:137], v[218:221], v[128:131]
	v_mfma_f32_16x16x32_bf16 v[124:127], v[142:145], v[218:221], v[124:127]
	v_mfma_f32_16x16x32_bf16 v[112:115], v[134:137], v[222:225], v[112:115]
	v_mfma_f32_16x16x32_bf16 v[108:111], v[142:145], v[222:225], v[108:111]
	v_mfma_f32_16x16x32_bf16 v[96:99], v[134:137], v[234:237], v[96:99]
	v_mfma_f32_16x16x32_bf16 v[92:95], v[142:145], v[234:237], v[92:95]
	v_mfma_f32_16x16x32_bf16 v[80:83], v[134:137], v[238:241], v[80:83]
	v_mfma_f32_16x16x32_bf16 v[76:79], v[142:145], v[238:241], v[76:79]
	v_mfma_f32_16x16x32_bf16 v[128:131], v[138:141], v[226:229], v[128:131]
	v_mfma_f32_16x16x32_bf16 v[124:127], v[146:149], v[226:229], v[124:127]
	v_mfma_f32_16x16x32_bf16 v[112:115], v[138:141], v[230:233], v[112:115]
	v_mfma_f32_16x16x32_bf16 v[108:111], v[146:149], v[230:233], v[108:111]
	v_mfma_f32_16x16x32_bf16 v[96:99], v[138:141], v[242:245], v[96:99]
	v_mfma_f32_16x16x32_bf16 v[92:95], v[146:149], v[242:245], v[92:95]
	v_mfma_f32_16x16x32_bf16 v[80:83], v[138:141], v[246:249], v[80:83]
	v_mfma_f32_16x16x32_bf16 v[76:79], v[146:149], v[246:249], v[76:79]
	v_mfma_f32_16x16x32_bf16 v[120:123], v[150:153], v[218:221], v[120:123]
	v_mfma_f32_16x16x32_bf16 v[116:119], v[178:181], v[218:221], v[116:119]
	v_mfma_f32_16x16x32_bf16 v[104:107], v[150:153], v[222:225], v[104:107]
	v_mfma_f32_16x16x32_bf16 v[100:103], v[178:181], v[222:225], v[100:103]
	v_mfma_f32_16x16x32_bf16 v[88:91], v[150:153], v[234:237], v[88:91]
	v_mfma_f32_16x16x32_bf16 v[84:87], v[178:181], v[234:237], v[84:87]
	v_mfma_f32_16x16x32_bf16 v[72:75], v[150:153], v[238:241], v[72:75]
	v_mfma_f32_16x16x32_bf16 v[68:71], v[178:181], v[238:241], v[68:71]
	v_mfma_f32_16x16x32_bf16 v[120:123], v[174:177], v[226:229], v[120:123]
	v_mfma_f32_16x16x32_bf16 v[116:119], v[182:185], v[226:229], v[116:119]
	v_mfma_f32_16x16x32_bf16 v[104:107], v[174:177], v[230:233], v[104:107]
	v_mfma_f32_16x16x32_bf16 v[100:103], v[182:185], v[230:233], v[100:103]
	v_mfma_f32_16x16x32_bf16 v[88:91], v[174:177], v[242:245], v[88:91]
	v_mfma_f32_16x16x32_bf16 v[84:87], v[182:185], v[242:245], v[84:87]
	v_mfma_f32_16x16x32_bf16 v[72:75], v[174:177], v[246:249], v[72:75]
	v_mfma_f32_16x16x32_bf16 v[68:71], v[182:185], v[246:249], v[68:71]
	s_barrier
	s_add_i32 s24, s70, s77
	v_lshl_add_u64 v[250:251], v[154:155], 0, s[48:49]
	s_mov_b32 m0, s24
	ds_read_b128 v[218:221], v207 offset:49152
	ds_read_b128 v[222:225], v207 offset:51200
	ds_read_b128 v[226:229], v208 offset:49152
	ds_read_b128 v[230:233], v208 offset:51200
	ds_read_b128 v[234:237], v207 offset:53248
	ds_read_b128 v[238:241], v207 offset:55296
	ds_read_b128 v[242:245], v208 offset:53248
	ds_read_b128 v[246:249], v208 offset:55296
	global_load_lds_dwordx4 v[250:251], off
	v_lshl_add_u64 v[250:251], v[154:155], 0, s[50:51]
	s_add_i32 m0, s24, 0x2000
	s_add_i32 s24, s71, s77
	global_load_lds_dwordx4 v[250:251], off
	v_lshl_add_u64 v[250:251], v[154:155], 0, s[52:53]
	s_mov_b32 m0, s24
	v_lshl_add_u64 v[154:155], v[154:155], 0, s[54:55]
	global_load_lds_dwordx4 v[250:251], off
	s_add_i32 m0, s24, 0x2000
	s_nop 0
	global_load_lds_dwordx4 v[154:155], off
	s_waitcnt vmcnt(4)
	s_waitcnt lgkmcnt(0)
	s_barrier
	v_mfma_f32_16x16x32_bf16 v[64:67], v[134:137], v[218:221], v[64:67]
	v_mfma_f32_16x16x32_bf16 v[60:63], v[142:145], v[218:221], v[60:63]
	v_mfma_f32_16x16x32_bf16 v[48:51], v[134:137], v[222:225], v[48:51]
	v_mfma_f32_16x16x32_bf16 v[44:47], v[142:145], v[222:225], v[44:47]
	v_mfma_f32_16x16x32_bf16 v[32:35], v[134:137], v[234:237], v[32:35]
	v_mfma_f32_16x16x32_bf16 v[28:31], v[142:145], v[234:237], v[28:31]
	v_mfma_f32_16x16x32_bf16 v[16:19], v[134:137], v[238:241], v[16:19]
	v_mfma_f32_16x16x32_bf16 v[12:15], v[142:145], v[238:241], v[12:15]
	v_mfma_f32_16x16x32_bf16 v[64:67], v[138:141], v[226:229], v[64:67]
	v_mfma_f32_16x16x32_bf16 v[60:63], v[146:149], v[226:229], v[60:63]
	v_mfma_f32_16x16x32_bf16 v[48:51], v[138:141], v[230:233], v[48:51]
	v_mfma_f32_16x16x32_bf16 v[44:47], v[146:149], v[230:233], v[44:47]
	v_mfma_f32_16x16x32_bf16 v[32:35], v[138:141], v[242:245], v[32:35]
	v_mfma_f32_16x16x32_bf16 v[28:31], v[146:149], v[242:245], v[28:31]
	v_mfma_f32_16x16x32_bf16 v[16:19], v[138:141], v[246:249], v[16:19]
	v_mfma_f32_16x16x32_bf16 v[12:15], v[146:149], v[246:249], v[12:15]
	v_mfma_f32_16x16x32_bf16 v[56:59], v[150:153], v[218:221], v[56:59]
	v_mfma_f32_16x16x32_bf16 v[52:55], v[178:181], v[218:221], v[52:55]
	v_mfma_f32_16x16x32_bf16 v[40:43], v[150:153], v[222:225], v[40:43]
	v_mfma_f32_16x16x32_bf16 v[36:39], v[178:181], v[222:225], v[36:39]
	v_mfma_f32_16x16x32_bf16 v[24:27], v[150:153], v[234:237], v[24:27]
	v_mfma_f32_16x16x32_bf16 v[20:23], v[178:181], v[234:237], v[20:23]
	v_mfma_f32_16x16x32_bf16 v[8:11], v[150:153], v[238:241], v[8:11]
	v_mfma_f32_16x16x32_bf16 v[4:7], v[178:181], v[238:241], v[4:7]
	v_mfma_f32_16x16x32_bf16 v[56:59], v[174:177], v[226:229], v[56:59]
	v_mfma_f32_16x16x32_bf16 v[52:55], v[182:185], v[226:229], v[52:55]
	v_mfma_f32_16x16x32_bf16 v[40:43], v[174:177], v[230:233], v[40:43]
	v_mfma_f32_16x16x32_bf16 v[36:39], v[182:185], v[230:233], v[36:39]
	v_mfma_f32_16x16x32_bf16 v[24:27], v[174:177], v[242:245], v[24:27]
	v_mfma_f32_16x16x32_bf16 v[20:23], v[182:185], v[242:245], v[20:23]
	v_mfma_f32_16x16x32_bf16 v[8:11], v[174:177], v[246:249], v[8:11]
	v_mfma_f32_16x16x32_bf16 v[4:7], v[182:185], v[246:249], v[4:7]
	s_barrier
	s_add_i32 s94, s94, 2
	s_add_u32 vcc_lo, vcc_lo, 0x100
	s_addc_u32 vcc_hi, vcc_hi, 0
	s_cmp_gt_u32 s94, 13
	s_cbranch_scc0 .LBB0_384
	s_and_b64 vcc, exec, s[56:57]
	s_cbranch_vccz .LBB0_387
	s_barrier

.LBB0_779:
	v_add_u32_e32 v4, s73, v159
	v_add_u32_e32 v6, s73, v173
	ds_read_b128 v[136:139], v4
	ds_read_b128 v[140:143], v6
	v_add_u32_e32 v4, s77, v159
	s_add_u32 s26, s28, s64
	v_add_u32_e32 v6, s77, v173
	ds_read_b128 v[180:183], v4
	ds_read_b128 v[196:199], v6
	v_add_u32_e32 v4, s79, v159
	s_addc_u32 s27, s29, s65
	v_add_u32_e32 v6, s79, v173
	ds_read_b128 v[200:203], v4
	ds_read_b128 v[204:207], v6
	v_add_u32_e32 v4, s80, v159
	s_add_u32 s26, s26, 0x100
	v_add_u32_e32 v6, s80, v173
	ds_read_b128 v[208:211], v4
	ds_read_b128 v[212:215], v6
	s_addc_u32 s27, s27, 0
	s_add_u32 s34, s93, s64
	s_addc_u32 s35, s94, s65
	s_cmpk_eq_i32 s64, 0xb00
	s_cselect_b32 s35, s63, s35
	s_cselect_b32 s34, s62, s34
	s_cselect_b32 s27, s1, s27
	s_cselect_b32 s26, s0, s26
	v_lshl_add_u64 v[6:7], v[170:171], 0, s[64:65]
	v_lshl_add_u64 v[184:185], v[6:7], 0, s[24:25]
	s_add_i32 m0, s66, 0x8000
	s_mov_b64 s[38:39], 0x30080
	ds_read_b128 v[216:219], v176
	ds_read_b128 v[220:223], v176 offset:2048
	ds_read_b128 v[224:227], v177
	ds_read_b128 v[228:231], v177 offset:2048
	ds_read_b128 v[232:235], v176 offset:4096
	ds_read_b128 v[236:239], v176 offset:6144
	ds_read_b128 v[240:243], v177 offset:4096
	ds_read_b128 v[244:247], v177 offset:6144
	global_load_lds_dwordx4 v[184:185], off
	v_lshl_add_u64 v[184:185], v[6:7], 0, s[38:39]
	s_add_i32 m0, s66, 0xa000
	s_mov_b64 s[38:39], 0x90080
	global_load_lds_dwordx4 v[184:185], off
	v_lshl_add_u64 v[184:185], v[6:7], 0, s[50:51]
	s_add_i32 m0, s66, 0xc000
	v_lshl_add_u64 v[6:7], v[6:7], 0, s[38:39]
	global_load_lds_dwordx4 v[184:185], off
	s_add_i32 m0, s66, 0xe000
	s_nop 0
	global_load_lds_dwordx4 v[6:7], off
	s_waitcnt vmcnt(8)
	s_waitcnt lgkmcnt(0)
	s_barrier
	v_mfma_f32_16x16x32_bf16 v[132:135], v[136:139], v[216:219], v[132:135]
	v_mfma_f32_16x16x32_bf16 v[128:131], v[180:183], v[216:219], v[128:131]
	v_mfma_f32_16x16x32_bf16 v[116:119], v[136:139], v[220:223], v[116:119]
	v_mfma_f32_16x16x32_bf16 v[112:115], v[180:183], v[220:223], v[112:115]
	v_mfma_f32_16x16x32_bf16 v[100:103], v[136:139], v[232:235], v[100:103]
	v_mfma_f32_16x16x32_bf16 v[96:99], v[180:183], v[232:235], v[96:99]
	v_mfma_f32_16x16x32_bf16 v[84:87], v[136:139], v[236:239], v[84:87]
	v_mfma_f32_16x16x32_bf16 v[80:83], v[180:183], v[236:239], v[80:83]
	v_mfma_f32_16x16x32_bf16 v[132:135], v[140:143], v[224:227], v[132:135]
	v_mfma_f32_16x16x32_bf16 v[128:131], v[196:199], v[224:227], v[128:131]
	v_mfma_f32_16x16x32_bf16 v[116:119], v[140:143], v[228:231], v[116:119]
	v_mfma_f32_16x16x32_bf16 v[112:115], v[196:199], v[228:231], v[112:115]
	v_mfma_f32_16x16x32_bf16 v[100:103], v[140:143], v[240:243], v[100:103]
	v_mfma_f32_16x16x32_bf16 v[96:99], v[196:199], v[240:243], v[96:99]
	v_mfma_f32_16x16x32_bf16 v[84:87], v[140:143], v[244:247], v[84:87]
	v_mfma_f32_16x16x32_bf16 v[80:83], v[196:199], v[244:247], v[80:83]
	v_mfma_f32_16x16x32_bf16 v[124:127], v[200:203], v[216:219], v[124:127]
	v_mfma_f32_16x16x32_bf16 v[120:123], v[208:211], v[216:219], v[120:123]
	v_mfma_f32_16x16x32_bf16 v[108:111], v[200:203], v[220:223], v[108:111]
	v_mfma_f32_16x16x32_bf16 v[104:107], v[208:211], v[220:223], v[104:107]
	v_mfma_f32_16x16x32_bf16 v[92:95], v[200:203], v[232:235], v[92:95]
	v_mfma_f32_16x16x32_bf16 v[88:91], v[208:211], v[232:235], v[88:91]
	v_mfma_f32_16x16x32_bf16 v[76:79], v[200:203], v[236:239], v[76:79]
	v_mfma_f32_16x16x32_bf16 v[72:75], v[208:211], v[236:239], v[72:75]
	v_mfma_f32_16x16x32_bf16 v[124:127], v[204:207], v[224:227], v[124:127]
	v_mfma_f32_16x16x32_bf16 v[120:123], v[212:215], v[224:227], v[120:123]
	v_mfma_f32_16x16x32_bf16 v[108:111], v[204:207], v[228:231], v[108:111]
	v_mfma_f32_16x16x32_bf16 v[104:107], v[212:215], v[228:231], v[104:107]
	v_mfma_f32_16x16x32_bf16 v[92:95], v[204:207], v[240:243], v[92:95]
	v_mfma_f32_16x16x32_bf16 v[88:91], v[212:215], v[240:243], v[88:91]
	v_mfma_f32_16x16x32_bf16 v[76:79], v[204:207], v[244:247], v[76:79]
	v_mfma_f32_16x16x32_bf16 v[72:75], v[212:215], v[244:247], v[72:75]
	s_barrier
	v_lshl_add_u64 v[184:185], s[34:35], 0, v[146:147]
	s_add_i32 s34, s73, s3
	s_mov_b32 m0, s34
	ds_read_b128 v[216:219], v176 offset:16384
	ds_read_b128 v[220:223], v176 offset:18432
	ds_read_b128 v[224:227], v177 offset:16384
	ds_read_b128 v[228:231], v177 offset:18432
	ds_read_b128 v[232:235], v176 offset:20480
	ds_read_b128 v[236:239], v176 offset:22528
	ds_read_b128 v[240:243], v177 offset:20480
	ds_read_b128 v[244:247], v177 offset:22528
	global_load_lds_dwordx4 v[184:185], off
	v_lshl_add_u64 v[6:7], v[184:185], 0, s[12:13]
	s_add_i32 m0, s34, 0x2000
	s_add_i32 s34, s79, s3
	global_load_lds_dwordx4 v[6:7], off
	v_lshl_add_u64 v[6:7], v[184:185], 0, s[14:15]
	s_mov_b32 m0, s34
	s_nop 0
	global_load_lds_dwordx4 v[6:7], off
	v_lshl_add_u64 v[6:7], v[184:185], 0, s[16:17]
	s_add_i32 m0, s34, 0x2000
	s_nop 0
	global_load_lds_dwordx4 v[6:7], off
	s_waitcnt vmcnt(4)
	s_waitcnt lgkmcnt(0)
	s_barrier
	v_mfma_f32_16x16x32_bf16 v[68:71], v[136:139], v[216:219], v[68:71]
	v_mfma_f32_16x16x32_bf16 v[64:67], v[180:183], v[216:219], v[64:67]
	v_mfma_f32_16x16x32_bf16 v[52:55], v[136:139], v[220:223], v[52:55]
	v_mfma_f32_16x16x32_bf16 v[48:51], v[180:183], v[220:223], v[48:51]
	v_mfma_f32_16x16x32_bf16 v[36:39], v[136:139], v[232:235], v[36:39]
	v_mfma_f32_16x16x32_bf16 v[32:35], v[180:183], v[232:235], v[32:35]
	v_mfma_f32_16x16x32_bf16 v[20:23], v[136:139], v[236:239], v[20:23]
	v_mfma_f32_16x16x32_bf16 v[16:19], v[180:183], v[236:239], v[16:19]
	v_mfma_f32_16x16x32_bf16 v[68:71], v[140:143], v[224:227], v[68:71]
	v_mfma_f32_16x16x32_bf16 v[64:67], v[196:199], v[224:227], v[64:67]
	v_mfma_f32_16x16x32_bf16 v[52:55], v[140:143], v[228:231], v[52:55]
	v_mfma_f32_16x16x32_bf16 v[48:51], v[196:199], v[228:231], v[48:51]
	v_mfma_f32_16x16x32_bf16 v[36:39], v[140:143], v[240:243], v[36:39]
	v_mfma_f32_16x16x32_bf16 v[32:35], v[196:199], v[240:243], v[32:35]
	v_mfma_f32_16x16x32_bf16 v[20:23], v[140:143], v[244:247], v[20:23]
	v_mfma_f32_16x16x32_bf16 v[16:19], v[196:199], v[244:247], v[16:19]
	v_mfma_f32_16x16x32_bf16 v[60:63], v[200:203], v[216:219], v[60:63]
	v_mfma_f32_16x16x32_bf16 v[56:59], v[208:211], v[216:219], v[56:59]
	v_mfma_f32_16x16x32_bf16 v[44:47], v[200:203], v[220:223], v[44:47]
	v_mfma_f32_16x16x32_bf16 v[40:43], v[208:211], v[220:223], v[40:43]
	v_mfma_f32_16x16x32_bf16 v[28:31], v[200:203], v[232:235], v[28:31]
	v_mfma_f32_16x16x32_bf16 v[24:27], v[208:211], v[232:235], v[24:27]
	v_mfma_f32_16x16x32_bf16 v[12:15], v[200:203], v[236:239], v[12:15]
	v_mfma_f32_16x16x32_bf16 v[6:9], v[208:211], v[236:239], v[8:11]
	v_mfma_f32_16x16x32_bf16 v[60:63], v[204:207], v[224:227], v[60:63]
	v_mfma_f32_16x16x32_bf16 v[56:59], v[212:215], v[224:227], v[56:59]
	v_mfma_f32_16x16x32_bf16 v[44:47], v[204:207], v[228:231], v[44:47]
	v_mfma_f32_16x16x32_bf16 v[40:43], v[212:215], v[228:231], v[40:43]
	v_mfma_f32_16x16x32_bf16 v[28:31], v[204:207], v[240:243], v[28:31]
	v_mfma_f32_16x16x32_bf16 v[24:27], v[212:215], v[240:243], v[24:27]
	v_mfma_f32_16x16x32_bf16 v[12:15], v[204:207], v[244:247], v[12:15]
	v_mfma_f32_16x16x32_bf16 v[6:9], v[212:215], v[244:247], v[6:9]
	s_barrier
	v_add_u32_e32 v4, s83, v159
	v_add_u32_e32 v10, s83, v173
	ds_read_b128 v[136:139], v4
	ds_read_b128 v[140:143], v10
	v_add_u32_e32 v4, s81, v159
	v_add_u32_e32 v10, s81, v173
	ds_read_b128 v[180:183], v4
	ds_read_b128 v[196:199], v10
	v_add_u32_e32 v4, s84, v159
	v_add_u32_e32 v10, s84, v173
	ds_read_b128 v[200:203], v4
	ds_read_b128 v[204:207], v10
	v_add_u32_e32 v4, s82, v159
	v_add_u32_e32 v10, s82, v173
	ds_read_b128 v[208:211], v4
	ds_read_b128 v[212:215], v10
	s_mov_b32 m0, s66
	v_lshl_add_u64 v[10:11], s[26:27], 0, v[144:145]
	ds_read_b128 v[216:219], v176 offset:32768
	ds_read_b128 v[220:223], v176 offset:34816
	ds_read_b128 v[224:227], v177 offset:32768
	ds_read_b128 v[228:231], v177 offset:34816
	ds_read_b128 v[232:235], v176 offset:36864
	ds_read_b128 v[236:239], v176 offset:38912
	ds_read_b128 v[240:243], v177 offset:36864
	ds_read_b128 v[244:247], v177 offset:38912
	global_load_lds_dwordx4 v[10:11], off
	v_lshl_add_u64 v[248:249], v[10:11], 0, s[18:19]
	s_mov_b32 m0, s67
	s_nop 0
	global_load_lds_dwordx4 v[248:249], off
	v_lshl_add_u64 v[248:249], v[10:11], 0, s[12:13]
	s_mov_b32 m0, s68
	v_lshl_add_u64 v[10:11], v[10:11], 0, s[20:21]
	global_load_lds_dwordx4 v[248:249], off
	s_mov_b32 m0, s69
	s_nop 0
	global_load_lds_dwordx4 v[10:11], off
	s_waitcnt vmcnt(8)
	s_waitcnt lgkmcnt(0)
	s_barrier
	v_mfma_f32_16x16x32_bf16 v[132:135], v[136:139], v[216:219], v[132:135]
	v_mfma_f32_16x16x32_bf16 v[128:131], v[180:183], v[216:219], v[128:131]
	v_mfma_f32_16x16x32_bf16 v[116:119], v[136:139], v[220:223], v[116:119]
	v_mfma_f32_16x16x32_bf16 v[112:115], v[180:183], v[220:223], v[112:115]
	v_mfma_f32_16x16x32_bf16 v[100:103], v[136:139], v[232:235], v[100:103]
	v_mfma_f32_16x16x32_bf16 v[96:99], v[180:183], v[232:235], v[96:99]
	v_mfma_f32_16x16x32_bf16 v[84:87], v[136:139], v[236:239], v[84:87]
	v_mfma_f32_16x16x32_bf16 v[80:83], v[180:183], v[236:239], v[80:83]
	v_mfma_f32_16x16x32_bf16 v[132:135], v[140:143], v[224:227], v[132:135]
	v_mfma_f32_16x16x32_bf16 v[128:131], v[196:199], v[224:227], v[128:131]
	v_mfma_f32_16x16x32_bf16 v[116:119], v[140:143], v[228:231], v[116:119]
	v_mfma_f32_16x16x32_bf16 v[112:115], v[196:199], v[228:231], v[112:115]
	v_mfma_f32_16x16x32_bf16 v[100:103], v[140:143], v[240:243], v[100:103]
	v_mfma_f32_16x16x32_bf16 v[96:99], v[196:199], v[240:243], v[96:99]
	v_mfma_f32_16x16x32_bf16 v[84:87], v[140:143], v[244:247], v[84:87]
	v_mfma_f32_16x16x32_bf16 v[80:83], v[196:199], v[244:247], v[80:83]
	v_mfma_f32_16x16x32_bf16 v[124:127], v[200:203], v[216:219], v[124:127]
	v_mfma_f32_16x16x32_bf16 v[120:123], v[208:211], v[216:219], v[120:123]
	v_mfma_f32_16x16x32_bf16 v[108:111], v[200:203], v[220:223], v[108:111]
	v_mfma_f32_16x16x32_bf16 v[104:107], v[208:211], v[220:223], v[104:107]
	v_mfma_f32_16x16x32_bf16 v[92:95], v[200:203], v[232:235], v[92:95]
	v_mfma_f32_16x16x32_bf16 v[88:91], v[208:211], v[232:235], v[88:91]
	v_mfma_f32_16x16x32_bf16 v[76:79], v[200:203], v[236:239], v[76:79]
	v_mfma_f32_16x16x32_bf16 v[72:75], v[208:211], v[236:239], v[72:75]
	v_mfma_f32_16x16x32_bf16 v[124:127], v[204:207], v[224:227], v[124:127]
	v_mfma_f32_16x16x32_bf16 v[120:123], v[212:215], v[224:227], v[120:123]
	v_mfma_f32_16x16x32_bf16 v[108:111], v[204:207], v[228:231], v[108:111]
	v_mfma_f32_16x16x32_bf16 v[104:107], v[212:215], v[228:231], v[104:107]
	v_mfma_f32_16x16x32_bf16 v[92:95], v[204:207], v[240:243], v[92:95]
	v_mfma_f32_16x16x32_bf16 v[88:91], v[212:215], v[240:243], v[88:91]
	v_mfma_f32_16x16x32_bf16 v[76:79], v[204:207], v[244:247], v[76:79]
	v_mfma_f32_16x16x32_bf16 v[72:75], v[212:215], v[244:247], v[72:75]
	s_barrier
	s_add_i32 s26, s83, s3
	v_lshl_add_u64 v[10:11], v[184:185], 0, s[24:25]
	s_mov_b32 m0, s26
	ds_read_b128 v[216:219], v176 offset:49152
	ds_read_b128 v[220:223], v176 offset:51200
	ds_read_b128 v[224:227], v177 offset:49152
	ds_read_b128 v[228:231], v177 offset:51200
	ds_read_b128 v[232:235], v176 offset:53248
	ds_read_b128 v[236:239], v176 offset:55296
	ds_read_b128 v[240:243], v177 offset:53248
	ds_read_b128 v[244:247], v177 offset:55296
	global_load_lds_dwordx4 v[10:11], off
	v_lshl_add_u64 v[10:11], v[184:185], 0, s[50:51]
	s_add_i32 m0, s26, 0x2000
	s_add_i32 s26, s84, s3
	global_load_lds_dwordx4 v[10:11], off
	v_lshl_add_u64 v[10:11], v[184:185], 0, s[52:53]
	s_mov_b32 m0, s26
	s_nop 0
	global_load_lds_dwordx4 v[10:11], off
	v_lshl_add_u64 v[10:11], v[184:185], 0, s[54:55]
	s_add_i32 m0, s26, 0x2000
	s_nop 0
	global_load_lds_dwordx4 v[10:11], off
	s_waitcnt vmcnt(4)
	s_waitcnt lgkmcnt(0)
	s_barrier
	v_mfma_f32_16x16x32_bf16 v[68:71], v[136:139], v[216:219], v[68:71]
	v_mfma_f32_16x16x32_bf16 v[64:67], v[180:183], v[216:219], v[64:67]
	v_mfma_f32_16x16x32_bf16 v[52:55], v[136:139], v[220:223], v[52:55]
	v_mfma_f32_16x16x32_bf16 v[48:51], v[180:183], v[220:223], v[48:51]
	v_mfma_f32_16x16x32_bf16 v[36:39], v[136:139], v[232:235], v[36:39]
	v_mfma_f32_16x16x32_bf16 v[32:35], v[180:183], v[232:235], v[32:35]
	v_mfma_f32_16x16x32_bf16 v[20:23], v[136:139], v[236:239], v[20:23]
	v_mfma_f32_16x16x32_bf16 v[16:19], v[180:183], v[236:239], v[16:19]
	v_mfma_f32_16x16x32_bf16 v[68:71], v[140:143], v[224:227], v[68:71]
	v_mfma_f32_16x16x32_bf16 v[64:67], v[196:199], v[224:227], v[64:67]
	v_mfma_f32_16x16x32_bf16 v[52:55], v[140:143], v[228:231], v[52:55]
	v_mfma_f32_16x16x32_bf16 v[48:51], v[196:199], v[228:231], v[48:51]
	v_mfma_f32_16x16x32_bf16 v[36:39], v[140:143], v[240:243], v[36:39]
	v_mfma_f32_16x16x32_bf16 v[32:35], v[196:199], v[240:243], v[32:35]
	v_mfma_f32_16x16x32_bf16 v[20:23], v[140:143], v[244:247], v[20:23]
	v_mfma_f32_16x16x32_bf16 v[16:19], v[196:199], v[244:247], v[16:19]
	v_mfma_f32_16x16x32_bf16 v[60:63], v[200:203], v[216:219], v[60:63]
	v_mfma_f32_16x16x32_bf16 v[56:59], v[208:211], v[216:219], v[56:59]
	v_mfma_f32_16x16x32_bf16 v[44:47], v[200:203], v[220:223], v[44:47]
	v_mfma_f32_16x16x32_bf16 v[40:43], v[208:211], v[220:223], v[40:43]
	v_mfma_f32_16x16x32_bf16 v[28:31], v[200:203], v[232:235], v[28:31]
	v_mfma_f32_16x16x32_bf16 v[24:27], v[208:211], v[232:235], v[24:27]
	v_mfma_f32_16x16x32_bf16 v[10:13], v[200:203], v[236:239], v[12:15]
	v_mfma_f32_16x16x32_bf16 v[6:9], v[208:211], v[236:239], v[6:9]
	v_mfma_f32_16x16x32_bf16 v[60:63], v[204:207], v[224:227], v[60:63]
	v_mfma_f32_16x16x32_bf16 v[56:59], v[212:215], v[224:227], v[56:59]
	v_mfma_f32_16x16x32_bf16 v[44:47], v[204:207], v[228:231], v[44:47]
	v_mfma_f32_16x16x32_bf16 v[40:43], v[212:215], v[228:231], v[40:43]
	v_mfma_f32_16x16x32_bf16 v[28:31], v[204:207], v[240:243], v[28:31]
	v_mfma_f32_16x16x32_bf16 v[24:27], v[212:215], v[240:243], v[24:27]
	v_mfma_f32_16x16x32_bf16 v[12:15], v[204:207], v[244:247], v[10:13]
	v_mfma_f32_16x16x32_bf16 v[8:11], v[212:215], v[244:247], v[6:9]
	s_barrier
	s_add_i32 s95, s95, 2
	s_add_u32 s64, s64, 0x100
	s_addc_u32 s65, s65, 0
	s_cmp_gt_u32 s95, 21
	s_cbranch_scc1 .LBB0_782

.LBB0_973:
	v_add_u32_e32 v133, s72, v163
	v_add_u32_e32 v140, s72, v164
	ds_read_b128 v[136:139], v133
	ds_read_b128 v[148:151], v140
	v_add_u32_e32 v133, s73, v163
	s_add_u32 s70, s28, s26
	v_add_u32_e32 v140, s73, v164
	s_waitcnt lgkmcnt(0)
	ds_read_b128 v[152:155], v133
	ds_read_b128 v[174:177], v140
	v_add_u32_e32 v133, s77, v163
	s_addc_u32 s71, s29, s27
	v_add_u32_e32 v140, s77, v164
	ds_read_b128 v[178:181], v133
	ds_read_b128 v[182:185], v140
	v_add_u32_e32 v133, s79, v163
	s_add_u32 s70, s70, 0x100
	v_add_u32_e32 v140, s79, v164
	ds_read_b128 v[196:199], v133
	ds_read_b128 v[200:203], v140
	s_addc_u32 s71, s71, 0
	s_add_u32 s86, s65, s26
	s_addc_u32 s87, s85, s27
	s_cmpk_eq_i32 s26, 0x700
	s_cselect_b32 s87, s61, s87
	s_cselect_b32 s86, s88, s86
	s_cselect_b32 s71, s54, s71
	s_cselect_b32 s70, s63, s70
	v_lshl_add_u64 v[140:141], v[134:135], 0, s[26:27]
	v_lshl_add_u64 v[160:161], v[140:141], 0, s[36:37]
	s_add_i32 m0, s5, 0x8000
	s_mov_b64 s[90:91], 0x20080
	ds_read_b128 v[204:207], v166
	ds_read_b128 v[208:211], v166 offset:2048
	ds_read_b128 v[212:215], v167
	ds_read_b128 v[216:219], v167 offset:2048
	ds_read_b128 v[220:223], v166 offset:4096
	ds_read_b128 v[224:227], v166 offset:6144
	ds_read_b128 v[228:231], v167 offset:4096
	ds_read_b128 v[232:235], v167 offset:6144
	global_load_lds_dwordx4 v[160:161], off
	v_lshl_add_u64 v[160:161], v[140:141], 0, s[90:91]
	s_add_i32 m0, s5, 0xa000
	s_mov_b64 s[90:91], 0x60080
	global_load_lds_dwordx4 v[160:161], off
	v_lshl_add_u64 v[160:161], v[140:141], 0, s[44:45]
	s_add_i32 m0, s5, 0xc000
	v_lshl_add_u64 v[140:141], v[140:141], 0, s[90:91]
	global_load_lds_dwordx4 v[160:161], off
	s_add_i32 m0, s5, 0xe000
	s_nop 0
	global_load_lds_dwordx4 v[140:141], off
	s_waitcnt vmcnt(8)
	s_waitcnt lgkmcnt(0)
	s_barrier
	v_mfma_f32_16x16x32_bf16 v[8:11], v[136:139], v[204:207], v[8:11]
	v_mfma_f32_16x16x32_bf16 v[4:7], v[152:155], v[204:207], v[4:7]
	v_mfma_f32_16x16x32_bf16 v[12:15], v[136:139], v[208:211], v[12:15]
	v_mfma_f32_16x16x32_bf16 v[16:19], v[152:155], v[208:211], v[16:19]
	v_mfma_f32_16x16x32_bf16 v[44:47], v[136:139], v[220:223], v[44:47]
	v_mfma_f32_16x16x32_bf16 v[36:39], v[152:155], v[220:223], v[36:39]
	v_mfma_f32_16x16x32_bf16 v[20:23], v[136:139], v[224:227], v[20:23]
	v_mfma_f32_16x16x32_bf16 v[24:27], v[152:155], v[224:227], v[24:27]
	v_mfma_f32_16x16x32_bf16 v[8:11], v[148:151], v[212:215], v[8:11]
	v_mfma_f32_16x16x32_bf16 v[4:7], v[174:177], v[212:215], v[4:7]
	v_mfma_f32_16x16x32_bf16 v[12:15], v[148:151], v[216:219], v[12:15]
	v_mfma_f32_16x16x32_bf16 v[16:19], v[174:177], v[216:219], v[16:19]
	v_mfma_f32_16x16x32_bf16 v[44:47], v[148:151], v[228:231], v[44:47]
	v_mfma_f32_16x16x32_bf16 v[36:39], v[174:177], v[228:231], v[36:39]
	v_mfma_f32_16x16x32_bf16 v[20:23], v[148:151], v[232:235], v[20:23]
	v_mfma_f32_16x16x32_bf16 v[24:27], v[174:177], v[232:235], v[24:27]
	v_mfma_f32_16x16x32_bf16 v[32:35], v[178:181], v[204:207], v[32:35]
	v_mfma_f32_16x16x32_bf16 v[28:31], v[196:199], v[204:207], v[28:31]
	v_mfma_f32_16x16x32_bf16 v[40:43], v[178:181], v[208:211], v[40:43]
	v_mfma_f32_16x16x32_bf16 v[52:55], v[196:199], v[208:211], v[52:55]
	v_mfma_f32_16x16x32_bf16 v[48:51], v[178:181], v[220:223], v[48:51]
	v_mfma_f32_16x16x32_bf16 v[60:63], v[196:199], v[220:223], v[60:63]
	v_mfma_f32_16x16x32_bf16 v[56:59], v[178:181], v[224:227], v[56:59]
	v_mfma_f32_16x16x32_bf16 v[64:67], v[196:199], v[224:227], v[64:67]
	v_mfma_f32_16x16x32_bf16 v[32:35], v[182:185], v[212:215], v[32:35]
	v_mfma_f32_16x16x32_bf16 v[28:31], v[200:203], v[212:215], v[28:31]
	v_mfma_f32_16x16x32_bf16 v[40:43], v[182:185], v[216:219], v[40:43]
	v_mfma_f32_16x16x32_bf16 v[52:55], v[200:203], v[216:219], v[52:55]
	v_mfma_f32_16x16x32_bf16 v[48:51], v[182:185], v[228:231], v[48:51]
	v_mfma_f32_16x16x32_bf16 v[60:63], v[200:203], v[228:231], v[60:63]
	v_mfma_f32_16x16x32_bf16 v[56:59], v[182:185], v[232:235], v[56:59]
	v_mfma_f32_16x16x32_bf16 v[64:67], v[200:203], v[232:235], v[64:67]
	s_barrier
	v_lshl_add_u64 v[140:141], s[86:87], 0, v[158:159]
	s_add_i32 s86, s72, s34
	s_mov_b32 m0, s86
	ds_read_b128 v[204:207], v166 offset:16384
	ds_read_b128 v[208:211], v166 offset:18432
	ds_read_b128 v[212:215], v167 offset:16384
	ds_read_b128 v[216:219], v167 offset:18432
	ds_read_b128 v[220:223], v166 offset:20480
	ds_read_b128 v[224:227], v166 offset:22528
	ds_read_b128 v[228:231], v167 offset:20480
	ds_read_b128 v[232:235], v167 offset:22528
	global_load_lds_dwordx4 v[140:141], off
	v_lshl_add_u64 v[160:161], v[140:141], 0, s[18:19]
	s_add_i32 m0, s86, 0x2000
	s_mov_b64 s[86:87], 0x10000
	global_load_lds_dwordx4 v[160:161], off
	v_lshl_add_u64 v[160:161], v[140:141], 0, s[86:87]
	s_add_i32 s86, s77, s34
	s_mov_b32 m0, s86
	s_nop 0
	global_load_lds_dwordx4 v[160:161], off
	v_lshl_add_u64 v[160:161], v[140:141], 0, s[20:21]
	s_add_i32 m0, s86, 0x2000
	s_nop 0
	global_load_lds_dwordx4 v[160:161], off
	s_waitcnt vmcnt(4)
	s_waitcnt lgkmcnt(0)
	s_barrier
	v_mfma_f32_16x16x32_bf16 v[68:71], v[136:139], v[204:207], v[68:71]
	v_mfma_f32_16x16x32_bf16 v[72:75], v[152:155], v[204:207], v[72:75]
	v_mfma_f32_16x16x32_bf16 v[92:95], v[136:139], v[208:211], v[92:95]
	v_mfma_f32_16x16x32_bf16 v[84:87], v[152:155], v[208:211], v[84:87]
	v_mfma_f32_16x16x32_bf16 v[76:79], v[136:139], v[220:223], v[76:79]
	v_mfma_f32_16x16x32_bf16 v[80:83], v[152:155], v[220:223], v[80:83]
	v_mfma_f32_16x16x32_bf16 v[116:119], v[136:139], v[224:227], v[116:119]
	v_mfma_f32_16x16x32_bf16 v[108:111], v[152:155], v[224:227], v[108:111]
	v_mfma_f32_16x16x32_bf16 v[68:71], v[148:151], v[212:215], v[68:71]
	v_mfma_f32_16x16x32_bf16 v[72:75], v[174:177], v[212:215], v[72:75]
	v_mfma_f32_16x16x32_bf16 v[92:95], v[148:151], v[216:219], v[92:95]
	v_mfma_f32_16x16x32_bf16 v[84:87], v[174:177], v[216:219], v[84:87]
	v_mfma_f32_16x16x32_bf16 v[76:79], v[148:151], v[228:231], v[76:79]
	v_mfma_f32_16x16x32_bf16 v[80:83], v[174:177], v[228:231], v[80:83]
	v_mfma_f32_16x16x32_bf16 v[116:119], v[148:151], v[232:235], v[116:119]
	v_mfma_f32_16x16x32_bf16 v[108:111], v[174:177], v[232:235], v[108:111]
	v_mfma_f32_16x16x32_bf16 v[88:91], v[178:181], v[204:207], v[88:91]
	v_mfma_f32_16x16x32_bf16 v[100:103], v[196:199], v[204:207], v[100:103]
	v_mfma_f32_16x16x32_bf16 v[96:99], v[178:181], v[208:211], v[96:99]
	v_mfma_f32_16x16x32_bf16 v[104:107], v[196:199], v[208:211], v[104:107]
	v_mfma_f32_16x16x32_bf16 v[112:115], v[178:181], v[220:223], v[112:115]
	v_mfma_f32_16x16x32_bf16 v[124:127], v[196:199], v[220:223], v[124:127]
	v_mfma_f32_16x16x32_bf16 v[120:123], v[178:181], v[224:227], v[120:123]
	v_mfma_f32_16x16x32_bf16 v[128:131], v[196:199], v[224:227], v[128:131]
	v_mfma_f32_16x16x32_bf16 v[88:91], v[182:185], v[212:215], v[88:91]
	v_mfma_f32_16x16x32_bf16 v[100:103], v[200:203], v[212:215], v[100:103]
	v_mfma_f32_16x16x32_bf16 v[96:99], v[182:185], v[216:219], v[96:99]
	v_mfma_f32_16x16x32_bf16 v[104:107], v[200:203], v[216:219], v[104:107]
	v_mfma_f32_16x16x32_bf16 v[112:115], v[182:185], v[228:231], v[112:115]
	v_mfma_f32_16x16x32_bf16 v[124:127], v[200:203], v[228:231], v[124:127]
	v_mfma_f32_16x16x32_bf16 v[120:123], v[182:185], v[232:235], v[120:123]
	v_mfma_f32_16x16x32_bf16 v[128:131], v[200:203], v[232:235], v[128:131]
	s_barrier
	v_add_u32_e32 v133, s82, v163
	v_add_u32_e32 v148, s82, v164
	ds_read_b128 v[136:139], v133
	ds_read_b128 v[148:151], v148
	v_add_u32_e32 v133, s80, v163
	v_add_u32_e32 v160, s80, v164
	ds_read_b128 v[152:155], v133
	ds_read_b128 v[174:177], v160
	v_add_u32_e32 v133, s83, v163
	v_add_u32_e32 v160, s83, v164
	ds_read_b128 v[178:181], v133
	ds_read_b128 v[182:185], v160
	v_add_u32_e32 v133, s81, v163
	v_add_u32_e32 v160, s81, v164
	ds_read_b128 v[196:199], v133
	ds_read_b128 v[200:203], v160
	s_mov_b32 m0, s5
	v_lshl_add_u64 v[160:161], s[70:71], 0, v[0:1]
	s_mov_b64 s[70:71], 0x20000
	ds_read_b128 v[204:207], v166 offset:32768
	ds_read_b128 v[208:211], v166 offset:34816
	ds_read_b128 v[212:215], v167 offset:32768
	ds_read_b128 v[216:219], v167 offset:34816
	ds_read_b128 v[220:223], v166 offset:36864
	ds_read_b128 v[224:227], v166 offset:38912
	ds_read_b128 v[228:231], v167 offset:36864
	ds_read_b128 v[232:235], v167 offset:38912
	global_load_lds_dwordx4 v[160:161], off
	v_lshl_add_u64 v[170:171], v[160:161], 0, s[70:71]
	s_mov_b32 m0, s17
	s_nop 0
	global_load_lds_dwordx4 v[170:171], off
	v_lshl_add_u64 v[170:171], v[160:161], 0, s[18:19]
	s_mov_b32 m0, s35
	v_lshl_add_u64 v[160:161], v[160:161], 0, s[22:23]
	global_load_lds_dwordx4 v[170:171], off
	s_mov_b32 m0, s38
	s_nop 0
	global_load_lds_dwordx4 v[160:161], off
	s_waitcnt vmcnt(8)
	s_waitcnt lgkmcnt(0)
	s_barrier
	v_mfma_f32_16x16x32_bf16 v[8:11], v[136:139], v[204:207], v[8:11]
	v_mfma_f32_16x16x32_bf16 v[4:7], v[152:155], v[204:207], v[4:7]
	v_mfma_f32_16x16x32_bf16 v[12:15], v[136:139], v[208:211], v[12:15]
	v_mfma_f32_16x16x32_bf16 v[16:19], v[152:155], v[208:211], v[16:19]
	v_mfma_f32_16x16x32_bf16 v[44:47], v[136:139], v[220:223], v[44:47]
	v_mfma_f32_16x16x32_bf16 v[36:39], v[152:155], v[220:223], v[36:39]
	v_mfma_f32_16x16x32_bf16 v[20:23], v[136:139], v[224:227], v[20:23]
	v_mfma_f32_16x16x32_bf16 v[24:27], v[152:155], v[224:227], v[24:27]
	v_mfma_f32_16x16x32_bf16 v[8:11], v[148:151], v[212:215], v[8:11]
	v_mfma_f32_16x16x32_bf16 v[4:7], v[174:177], v[212:215], v[4:7]
	v_mfma_f32_16x16x32_bf16 v[12:15], v[148:151], v[216:219], v[12:15]
	v_mfma_f32_16x16x32_bf16 v[16:19], v[174:177], v[216:219], v[16:19]
	v_mfma_f32_16x16x32_bf16 v[44:47], v[148:151], v[228:231], v[44:47]
	v_mfma_f32_16x16x32_bf16 v[36:39], v[174:177], v[228:231], v[36:39]
	v_mfma_f32_16x16x32_bf16 v[20:23], v[148:151], v[232:235], v[20:23]
	v_mfma_f32_16x16x32_bf16 v[24:27], v[174:177], v[232:235], v[24:27]
	v_mfma_f32_16x16x32_bf16 v[32:35], v[178:181], v[204:207], v[32:35]
	v_mfma_f32_16x16x32_bf16 v[28:31], v[196:199], v[204:207], v[28:31]
	v_mfma_f32_16x16x32_bf16 v[40:43], v[178:181], v[208:211], v[40:43]
	v_mfma_f32_16x16x32_bf16 v[52:55], v[196:199], v[208:211], v[52:55]
	v_mfma_f32_16x16x32_bf16 v[48:51], v[178:181], v[220:223], v[48:51]
	v_mfma_f32_16x16x32_bf16 v[60:63], v[196:199], v[220:223], v[60:63]
	v_mfma_f32_16x16x32_bf16 v[56:59], v[178:181], v[224:227], v[56:59]
	v_mfma_f32_16x16x32_bf16 v[64:67], v[196:199], v[224:227], v[64:67]
	v_mfma_f32_16x16x32_bf16 v[32:35], v[182:185], v[212:215], v[32:35]
	v_mfma_f32_16x16x32_bf16 v[28:31], v[200:203], v[212:215], v[28:31]
	v_mfma_f32_16x16x32_bf16 v[40:43], v[182:185], v[216:219], v[40:43]
	v_mfma_f32_16x16x32_bf16 v[52:55], v[200:203], v[216:219], v[52:55]
	v_mfma_f32_16x16x32_bf16 v[48:51], v[182:185], v[228:231], v[48:51]
	v_mfma_f32_16x16x32_bf16 v[60:63], v[200:203], v[228:231], v[60:63]
	v_mfma_f32_16x16x32_bf16 v[56:59], v[182:185], v[232:235], v[56:59]
	v_mfma_f32_16x16x32_bf16 v[64:67], v[200:203], v[232:235], v[64:67]
	s_barrier
	s_add_i32 s70, s82, s34
	v_lshl_add_u64 v[160:161], v[140:141], 0, s[36:37]
	s_mov_b32 m0, s70
	ds_read_b128 v[204:207], v166 offset:49152
	ds_read_b128 v[208:211], v166 offset:51200
	ds_read_b128 v[212:215], v167 offset:49152
	ds_read_b128 v[216:219], v167 offset:51200
	ds_read_b128 v[220:223], v166 offset:53248
	ds_read_b128 v[224:227], v166 offset:55296
	ds_read_b128 v[228:231], v167 offset:53248
	ds_read_b128 v[232:235], v167 offset:55296
	global_load_lds_dwordx4 v[160:161], off
	v_lshl_add_u64 v[160:161], v[140:141], 0, s[44:45]
	s_add_i32 m0, s70, 0x2000
	s_add_i32 s70, s83, s34
	global_load_lds_dwordx4 v[160:161], off
	v_lshl_add_u64 v[160:161], v[140:141], 0, s[46:47]
	s_mov_b32 m0, s70
	v_lshl_add_u64 v[140:141], v[140:141], 0, s[50:51]
	global_load_lds_dwordx4 v[160:161], off
	s_add_i32 m0, s70, 0x2000
	s_nop 0
	global_load_lds_dwordx4 v[140:141], off
	s_waitcnt vmcnt(4)
	s_waitcnt lgkmcnt(0)
	s_barrier
	v_mfma_f32_16x16x32_bf16 v[68:71], v[136:139], v[204:207], v[68:71]
	v_mfma_f32_16x16x32_bf16 v[72:75], v[152:155], v[204:207], v[72:75]
	v_mfma_f32_16x16x32_bf16 v[92:95], v[136:139], v[208:211], v[92:95]
	v_mfma_f32_16x16x32_bf16 v[84:87], v[152:155], v[208:211], v[84:87]
	v_mfma_f32_16x16x32_bf16 v[76:79], v[136:139], v[220:223], v[76:79]
	v_mfma_f32_16x16x32_bf16 v[80:83], v[152:155], v[220:223], v[80:83]
	v_mfma_f32_16x16x32_bf16 v[116:119], v[136:139], v[224:227], v[116:119]
	v_mfma_f32_16x16x32_bf16 v[108:111], v[152:155], v[224:227], v[108:111]
	v_mfma_f32_16x16x32_bf16 v[68:71], v[148:151], v[212:215], v[68:71]
	v_mfma_f32_16x16x32_bf16 v[72:75], v[174:177], v[212:215], v[72:75]
	v_mfma_f32_16x16x32_bf16 v[92:95], v[148:151], v[216:219], v[92:95]
	v_mfma_f32_16x16x32_bf16 v[84:87], v[174:177], v[216:219], v[84:87]
	v_mfma_f32_16x16x32_bf16 v[76:79], v[148:151], v[228:231], v[76:79]
	v_mfma_f32_16x16x32_bf16 v[80:83], v[174:177], v[228:231], v[80:83]
	v_mfma_f32_16x16x32_bf16 v[116:119], v[148:151], v[232:235], v[116:119]
	v_mfma_f32_16x16x32_bf16 v[108:111], v[174:177], v[232:235], v[108:111]
	v_mfma_f32_16x16x32_bf16 v[88:91], v[178:181], v[204:207], v[88:91]
	v_mfma_f32_16x16x32_bf16 v[100:103], v[196:199], v[204:207], v[100:103]
	v_mfma_f32_16x16x32_bf16 v[96:99], v[178:181], v[208:211], v[96:99]
	v_mfma_f32_16x16x32_bf16 v[104:107], v[196:199], v[208:211], v[104:107]
	v_mfma_f32_16x16x32_bf16 v[112:115], v[178:181], v[220:223], v[112:115]
	v_mfma_f32_16x16x32_bf16 v[124:127], v[196:199], v[220:223], v[124:127]
	v_mfma_f32_16x16x32_bf16 v[120:123], v[178:181], v[224:227], v[120:123]
	v_mfma_f32_16x16x32_bf16 v[128:131], v[196:199], v[224:227], v[128:131]
	v_mfma_f32_16x16x32_bf16 v[88:91], v[182:185], v[212:215], v[88:91]
	v_mfma_f32_16x16x32_bf16 v[100:103], v[200:203], v[212:215], v[100:103]
	v_mfma_f32_16x16x32_bf16 v[96:99], v[182:185], v[216:219], v[96:99]
	v_mfma_f32_16x16x32_bf16 v[104:107], v[200:203], v[216:219], v[104:107]
	v_mfma_f32_16x16x32_bf16 v[112:115], v[182:185], v[228:231], v[112:115]
	v_mfma_f32_16x16x32_bf16 v[124:127], v[200:203], v[228:231], v[124:127]
	v_mfma_f32_16x16x32_bf16 v[120:123], v[182:185], v[232:235], v[120:123]
	v_mfma_f32_16x16x32_bf16 v[128:131], v[200:203], v[232:235], v[128:131]
	s_barrier
	s_add_i32 s89, s89, 2
	s_add_u32 s26, s26, 0x100
	s_addc_u32 s27, s27, 0
	s_cmp_gt_u32 s89, 13
	s_cbranch_scc0 .LBB0_973
	s_and_b64 vcc, exec, s[52:53]
	s_cbranch_vccz .LBB0_976
	s_barrier

.LBB0_1135:
	ds_read_b128 v[168:171], v145
	ds_read_b128 v[174:177], v146
	ds_read_b128 v[178:181], v147
	ds_read_b128 v[182:185], v148
	ds_read_b128 v[194:197], v149
	ds_read_b128 v[198:201], v150
	ds_read_b128 v[202:205], v151
	ds_read_b128 v[206:209], v152
	s_add_u32 s70, s26, s68
	s_addc_u32 s71, s27, s69
	s_add_u32 s70, s70, 0x100
	s_addc_u32 s71, s71, 0
	s_add_u32 s84, s81, s68
	s_addc_u32 s85, s82, s69
	s_cmpk_eq_i32 s68, 0x700
	s_cselect_b32 s85, s59, s85
	s_cselect_b32 s84, s80, s84
	s_cselect_b32 s71, s57, s71
	s_cselect_b32 s70, s79, s70
	v_lshl_add_u64 v[140:141], v[138:139], 0, s[68:69]
	v_lshl_add_u64 v[242:243], v[140:141], 0, s[22:23]
	s_add_i32 m0, s34, 0x8000
	s_mov_b64 s[86:87], 0x20080
	ds_read_b128 v[210:213], v153
	ds_read_b128 v[214:217], v153 offset:2048
	ds_read_b128 v[218:221], v154
	ds_read_b128 v[222:225], v154 offset:2048
	ds_read_b128 v[226:229], v153 offset:4096
	ds_read_b128 v[230:233], v153 offset:6144
	ds_read_b128 v[234:237], v154 offset:4096
	ds_read_b128 v[238:241], v154 offset:6144
	global_load_lds_dwordx4 v[242:243], off
	v_lshl_add_u64 v[242:243], v[140:141], 0, s[86:87]
	s_add_i32 m0, s34, 0xa000
	s_mov_b64 s[86:87], 0x60080
	global_load_lds_dwordx4 v[242:243], off
	v_lshl_add_u64 v[242:243], v[140:141], 0, s[24:25]
	s_add_i32 m0, s34, 0xc000
	v_lshl_add_u64 v[140:141], v[140:141], 0, s[86:87]
	global_load_lds_dwordx4 v[242:243], off
	s_add_i32 m0, s34, 0xe000
	s_nop 0
	global_load_lds_dwordx4 v[140:141], off
	s_waitcnt vmcnt(8)
	s_waitcnt lgkmcnt(0)
	s_barrier
	v_mfma_f32_16x16x32_bf16 v[128:131], v[168:171], v[210:213], v[128:131]
	v_mfma_f32_16x16x32_bf16 v[124:127], v[178:181], v[210:213], v[124:127]
	v_mfma_f32_16x16x32_bf16 v[112:115], v[168:171], v[214:217], v[112:115]
	v_mfma_f32_16x16x32_bf16 v[108:111], v[178:181], v[214:217], v[108:111]
	v_mfma_f32_16x16x32_bf16 v[96:99], v[168:171], v[226:229], v[96:99]
	v_mfma_f32_16x16x32_bf16 v[92:95], v[178:181], v[226:229], v[92:95]
	v_mfma_f32_16x16x32_bf16 v[80:83], v[168:171], v[230:233], v[80:83]
	v_mfma_f32_16x16x32_bf16 v[76:79], v[178:181], v[230:233], v[76:79]
	v_mfma_f32_16x16x32_bf16 v[128:131], v[174:177], v[218:221], v[128:131]
	v_mfma_f32_16x16x32_bf16 v[124:127], v[182:185], v[218:221], v[124:127]
	v_mfma_f32_16x16x32_bf16 v[112:115], v[174:177], v[222:225], v[112:115]
	v_mfma_f32_16x16x32_bf16 v[108:111], v[182:185], v[222:225], v[108:111]
	v_mfma_f32_16x16x32_bf16 v[96:99], v[174:177], v[234:237], v[96:99]
	v_mfma_f32_16x16x32_bf16 v[92:95], v[182:185], v[234:237], v[92:95]
	v_mfma_f32_16x16x32_bf16 v[80:83], v[174:177], v[238:241], v[80:83]
	v_mfma_f32_16x16x32_bf16 v[76:79], v[182:185], v[238:241], v[76:79]
	v_mfma_f32_16x16x32_bf16 v[120:123], v[194:197], v[210:213], v[120:123]
	v_mfma_f32_16x16x32_bf16 v[116:119], v[202:205], v[210:213], v[116:119]
	v_mfma_f32_16x16x32_bf16 v[104:107], v[194:197], v[214:217], v[104:107]
	v_mfma_f32_16x16x32_bf16 v[100:103], v[202:205], v[214:217], v[100:103]
	v_mfma_f32_16x16x32_bf16 v[88:91], v[194:197], v[226:229], v[88:91]
	v_mfma_f32_16x16x32_bf16 v[84:87], v[202:205], v[226:229], v[84:87]
	v_mfma_f32_16x16x32_bf16 v[72:75], v[194:197], v[230:233], v[72:75]
	v_mfma_f32_16x16x32_bf16 v[68:71], v[202:205], v[230:233], v[68:71]
	v_mfma_f32_16x16x32_bf16 v[120:123], v[198:201], v[218:221], v[120:123]
	v_mfma_f32_16x16x32_bf16 v[116:119], v[206:209], v[218:221], v[116:119]
	v_mfma_f32_16x16x32_bf16 v[104:107], v[198:201], v[222:225], v[104:107]
	v_mfma_f32_16x16x32_bf16 v[100:103], v[206:209], v[222:225], v[100:103]
	v_mfma_f32_16x16x32_bf16 v[88:91], v[198:201], v[234:237], v[88:91]
	v_mfma_f32_16x16x32_bf16 v[84:87], v[206:209], v[234:237], v[84:87]
	v_mfma_f32_16x16x32_bf16 v[72:75], v[198:201], v[238:241], v[72:75]
	v_mfma_f32_16x16x32_bf16 v[68:71], v[206:209], v[238:241], v[68:71]
	s_barrier
	v_lshl_add_u64 v[140:141], s[84:85], 0, v[158:159]
	s_add_i32 s84, s67, s3
	s_mov_b32 m0, s84
	ds_read_b128 v[210:213], v153 offset:16384
	ds_read_b128 v[214:217], v153 offset:18432
	ds_read_b128 v[218:221], v154 offset:16384
	ds_read_b128 v[222:225], v154 offset:18432
	ds_read_b128 v[226:229], v153 offset:20480
	ds_read_b128 v[230:233], v153 offset:22528
	ds_read_b128 v[234:237], v154 offset:20480
	ds_read_b128 v[238:241], v154 offset:22528
	global_load_lds_dwordx4 v[140:141], off
	v_lshl_add_u64 v[242:243], v[140:141], 0, s[0:1]
	s_add_i32 m0, s84, 0x2000
	s_add_i32 s84, s72, s3
	global_load_lds_dwordx4 v[242:243], off
	v_lshl_add_u64 v[242:243], v[140:141], 0, s[12:13]
	s_mov_b32 m0, s84
	s_nop 0
	global_load_lds_dwordx4 v[242:243], off
	v_lshl_add_u64 v[242:243], v[140:141], 0, s[14:15]
	s_add_i32 m0, s84, 0x2000
	s_nop 0
	global_load_lds_dwordx4 v[242:243], off
	s_waitcnt vmcnt(4)
	s_waitcnt lgkmcnt(0)
	s_barrier
	v_mfma_f32_16x16x32_bf16 v[64:67], v[168:171], v[210:213], v[64:67]
	v_mfma_f32_16x16x32_bf16 v[60:63], v[178:181], v[210:213], v[60:63]
	v_mfma_f32_16x16x32_bf16 v[48:51], v[168:171], v[214:217], v[48:51]
	v_mfma_f32_16x16x32_bf16 v[44:47], v[178:181], v[214:217], v[44:47]
	v_mfma_f32_16x16x32_bf16 v[32:35], v[168:171], v[226:229], v[32:35]
	v_mfma_f32_16x16x32_bf16 v[28:31], v[178:181], v[226:229], v[28:31]
	v_mfma_f32_16x16x32_bf16 v[16:19], v[168:171], v[230:233], v[16:19]
	v_mfma_f32_16x16x32_bf16 v[12:15], v[178:181], v[230:233], v[12:15]
	v_mfma_f32_16x16x32_bf16 v[64:67], v[174:177], v[218:221], v[64:67]
	v_mfma_f32_16x16x32_bf16 v[60:63], v[182:185], v[218:221], v[60:63]
	v_mfma_f32_16x16x32_bf16 v[48:51], v[174:177], v[222:225], v[48:51]
	v_mfma_f32_16x16x32_bf16 v[44:47], v[182:185], v[222:225], v[44:47]
	v_mfma_f32_16x16x32_bf16 v[32:35], v[174:177], v[234:237], v[32:35]
	v_mfma_f32_16x16x32_bf16 v[28:31], v[182:185], v[234:237], v[28:31]
	v_mfma_f32_16x16x32_bf16 v[16:19], v[174:177], v[238:241], v[16:19]
	v_mfma_f32_16x16x32_bf16 v[12:15], v[182:185], v[238:241], v[12:15]
	v_mfma_f32_16x16x32_bf16 v[56:59], v[194:197], v[210:213], v[56:59]
	v_mfma_f32_16x16x32_bf16 v[52:55], v[202:205], v[210:213], v[52:55]
	v_mfma_f32_16x16x32_bf16 v[40:43], v[194:197], v[214:217], v[40:43]
	v_mfma_f32_16x16x32_bf16 v[36:39], v[202:205], v[214:217], v[36:39]
	v_mfma_f32_16x16x32_bf16 v[24:27], v[194:197], v[226:229], v[24:27]
	v_mfma_f32_16x16x32_bf16 v[20:23], v[202:205], v[226:229], v[20:23]
	v_mfma_f32_16x16x32_bf16 v[8:11], v[194:197], v[230:233], v[8:11]
	v_mfma_f32_16x16x32_bf16 v[4:7], v[202:205], v[230:233], v[4:7]
	v_mfma_f32_16x16x32_bf16 v[56:59], v[198:201], v[218:221], v[56:59]
	v_mfma_f32_16x16x32_bf16 v[52:55], v[206:209], v[218:221], v[52:55]
	v_mfma_f32_16x16x32_bf16 v[40:43], v[198:201], v[222:225], v[40:43]
	v_mfma_f32_16x16x32_bf16 v[36:39], v[206:209], v[222:225], v[36:39]
	v_mfma_f32_16x16x32_bf16 v[24:27], v[198:201], v[234:237], v[24:27]
	v_mfma_f32_16x16x32_bf16 v[20:23], v[206:209], v[234:237], v[20:23]
	v_mfma_f32_16x16x32_bf16 v[8:11], v[198:201], v[238:241], v[8:11]
	v_mfma_f32_16x16x32_bf16 v[4:7], v[206:209], v[238:241], v[4:7]
	s_barrier
	ds_read_b128 v[168:171], v163
	ds_read_b128 v[174:177], v164
	ds_read_b128 v[178:181], v155
	ds_read_b128 v[182:185], v160
	ds_read_b128 v[194:197], v165
	ds_read_b128 v[198:201], v166
	ds_read_b128 v[202:205], v161
	ds_read_b128 v[206:209], v162
	s_mov_b32 m0, s34
	v_lshl_add_u64 v[242:243], s[70:71], 0, v[0:1]
	ds_read_b128 v[210:213], v153 offset:32768
	ds_read_b128 v[214:217], v153 offset:34816
	ds_read_b128 v[218:221], v154 offset:32768
	ds_read_b128 v[222:225], v154 offset:34816
	ds_read_b128 v[226:229], v153 offset:36864
	ds_read_b128 v[230:233], v153 offset:38912
	ds_read_b128 v[234:237], v154 offset:36864
	ds_read_b128 v[238:241], v154 offset:38912
	global_load_lds_dwordx4 v[242:243], off
	v_lshl_add_u64 v[244:245], v[242:243], 0, s[16:17]
	s_mov_b32 m0, s35
	s_nop 0
	global_load_lds_dwordx4 v[244:245], off
	v_lshl_add_u64 v[244:245], v[242:243], 0, s[0:1]
	s_mov_b32 m0, s38
	v_lshl_add_u64 v[242:243], v[242:243], 0, s[18:19]
	global_load_lds_dwordx4 v[244:245], off
	s_mov_b32 m0, s39
	s_nop 0
	global_load_lds_dwordx4 v[242:243], off
	s_waitcnt vmcnt(8)
	s_waitcnt lgkmcnt(0)
	s_barrier
	v_mfma_f32_16x16x32_bf16 v[128:131], v[168:171], v[210:213], v[128:131]
	v_mfma_f32_16x16x32_bf16 v[124:127], v[178:181], v[210:213], v[124:127]
	v_mfma_f32_16x16x32_bf16 v[112:115], v[168:171], v[214:217], v[112:115]
	v_mfma_f32_16x16x32_bf16 v[108:111], v[178:181], v[214:217], v[108:111]
	v_mfma_f32_16x16x32_bf16 v[96:99], v[168:171], v[226:229], v[96:99]
	v_mfma_f32_16x16x32_bf16 v[92:95], v[178:181], v[226:229], v[92:95]
	v_mfma_f32_16x16x32_bf16 v[80:83], v[168:171], v[230:233], v[80:83]
	v_mfma_f32_16x16x32_bf16 v[76:79], v[178:181], v[230:233], v[76:79]
	v_mfma_f32_16x16x32_bf16 v[128:131], v[174:177], v[218:221], v[128:131]
	v_mfma_f32_16x16x32_bf16 v[124:127], v[182:185], v[218:221], v[124:127]
	v_mfma_f32_16x16x32_bf16 v[112:115], v[174:177], v[222:225], v[112:115]
	v_mfma_f32_16x16x32_bf16 v[108:111], v[182:185], v[222:225], v[108:111]
	v_mfma_f32_16x16x32_bf16 v[96:99], v[174:177], v[234:237], v[96:99]
	v_mfma_f32_16x16x32_bf16 v[92:95], v[182:185], v[234:237], v[92:95]
	v_mfma_f32_16x16x32_bf16 v[80:83], v[174:177], v[238:241], v[80:83]
	v_mfma_f32_16x16x32_bf16 v[76:79], v[182:185], v[238:241], v[76:79]
	v_mfma_f32_16x16x32_bf16 v[120:123], v[194:197], v[210:213], v[120:123]
	v_mfma_f32_16x16x32_bf16 v[116:119], v[202:205], v[210:213], v[116:119]
	v_mfma_f32_16x16x32_bf16 v[104:107], v[194:197], v[214:217], v[104:107]
	v_mfma_f32_16x16x32_bf16 v[100:103], v[202:205], v[214:217], v[100:103]
	v_mfma_f32_16x16x32_bf16 v[88:91], v[194:197], v[226:229], v[88:91]
	v_mfma_f32_16x16x32_bf16 v[84:87], v[202:205], v[226:229], v[84:87]
	v_mfma_f32_16x16x32_bf16 v[72:75], v[194:197], v[230:233], v[72:75]
	v_mfma_f32_16x16x32_bf16 v[68:71], v[202:205], v[230:233], v[68:71]
	v_mfma_f32_16x16x32_bf16 v[120:123], v[198:201], v[218:221], v[120:123]
	v_mfma_f32_16x16x32_bf16 v[116:119], v[206:209], v[218:221], v[116:119]
	v_mfma_f32_16x16x32_bf16 v[104:107], v[198:201], v[222:225], v[104:107]
	v_mfma_f32_16x16x32_bf16 v[100:103], v[206:209], v[222:225], v[100:103]
	v_mfma_f32_16x16x32_bf16 v[88:91], v[198:201], v[234:237], v[88:91]
	v_mfma_f32_16x16x32_bf16 v[84:87], v[206:209], v[234:237], v[84:87]
	v_mfma_f32_16x16x32_bf16 v[72:75], v[198:201], v[238:241], v[72:75]
	v_mfma_f32_16x16x32_bf16 v[68:71], v[206:209], v[238:241], v[68:71]
	s_barrier
	s_add_i32 s70, s73, s3
	v_lshl_add_u64 v[242:243], v[140:141], 0, s[22:23]
	s_mov_b32 m0, s70
	ds_read_b128 v[210:213], v153 offset:49152
	ds_read_b128 v[214:217], v153 offset:51200
	ds_read_b128 v[218:221], v154 offset:49152
	ds_read_b128 v[222:225], v154 offset:51200
	ds_read_b128 v[226:229], v153 offset:53248
	ds_read_b128 v[230:233], v153 offset:55296
	ds_read_b128 v[234:237], v154 offset:53248
	ds_read_b128 v[238:241], v154 offset:55296
	global_load_lds_dwordx4 v[242:243], off
	v_lshl_add_u64 v[242:243], v[140:141], 0, s[24:25]
	s_add_i32 m0, s70, 0x2000
	s_add_i32 s70, s77, s3
	global_load_lds_dwordx4 v[242:243], off
	v_lshl_add_u64 v[242:243], v[140:141], 0, s[28:29]
	s_mov_b32 m0, s70
	v_lshl_add_u64 v[140:141], v[140:141], 0, s[36:37]
	global_load_lds_dwordx4 v[242:243], off
	s_add_i32 m0, s70, 0x2000
	s_nop 0
	global_load_lds_dwordx4 v[140:141], off
	s_waitcnt vmcnt(4)
	s_waitcnt lgkmcnt(0)
	s_barrier
	v_mfma_f32_16x16x32_bf16 v[64:67], v[168:171], v[210:213], v[64:67]
	v_mfma_f32_16x16x32_bf16 v[60:63], v[178:181], v[210:213], v[60:63]
	v_mfma_f32_16x16x32_bf16 v[48:51], v[168:171], v[214:217], v[48:51]
	v_mfma_f32_16x16x32_bf16 v[44:47], v[178:181], v[214:217], v[44:47]
	v_mfma_f32_16x16x32_bf16 v[32:35], v[168:171], v[226:229], v[32:35]
	v_mfma_f32_16x16x32_bf16 v[28:31], v[178:181], v[226:229], v[28:31]
	v_mfma_f32_16x16x32_bf16 v[16:19], v[168:171], v[230:233], v[16:19]
	v_mfma_f32_16x16x32_bf16 v[12:15], v[178:181], v[230:233], v[12:15]
	v_mfma_f32_16x16x32_bf16 v[64:67], v[174:177], v[218:221], v[64:67]
	v_mfma_f32_16x16x32_bf16 v[60:63], v[182:185], v[218:221], v[60:63]
	v_mfma_f32_16x16x32_bf16 v[48:51], v[174:177], v[222:225], v[48:51]
	v_mfma_f32_16x16x32_bf16 v[44:47], v[182:185], v[222:225], v[44:47]
	v_mfma_f32_16x16x32_bf16 v[32:35], v[174:177], v[234:237], v[32:35]
	v_mfma_f32_16x16x32_bf16 v[28:31], v[182:185], v[234:237], v[28:31]
	v_mfma_f32_16x16x32_bf16 v[16:19], v[174:177], v[238:241], v[16:19]
	v_mfma_f32_16x16x32_bf16 v[12:15], v[182:185], v[238:241], v[12:15]
	v_mfma_f32_16x16x32_bf16 v[56:59], v[194:197], v[210:213], v[56:59]
	v_mfma_f32_16x16x32_bf16 v[52:55], v[202:205], v[210:213], v[52:55]
	v_mfma_f32_16x16x32_bf16 v[40:43], v[194:197], v[214:217], v[40:43]
	v_mfma_f32_16x16x32_bf16 v[36:39], v[202:205], v[214:217], v[36:39]
	v_mfma_f32_16x16x32_bf16 v[24:27], v[194:197], v[226:229], v[24:27]
	v_mfma_f32_16x16x32_bf16 v[20:23], v[202:205], v[226:229], v[20:23]
	v_mfma_f32_16x16x32_bf16 v[8:11], v[194:197], v[230:233], v[8:11]
	v_mfma_f32_16x16x32_bf16 v[4:7], v[202:205], v[230:233], v[4:7]
	v_mfma_f32_16x16x32_bf16 v[56:59], v[198:201], v[218:221], v[56:59]
	v_mfma_f32_16x16x32_bf16 v[52:55], v[206:209], v[218:221], v[52:55]
	v_mfma_f32_16x16x32_bf16 v[40:43], v[198:201], v[222:225], v[40:43]
	v_mfma_f32_16x16x32_bf16 v[36:39], v[206:209], v[222:225], v[36:39]
	v_mfma_f32_16x16x32_bf16 v[24:27], v[198:201], v[234:237], v[24:27]
	v_mfma_f32_16x16x32_bf16 v[20:23], v[206:209], v[234:237], v[20:23]
	v_mfma_f32_16x16x32_bf16 v[8:11], v[198:201], v[238:241], v[8:11]
	v_mfma_f32_16x16x32_bf16 v[4:7], v[206:209], v[238:241], v[4:7]
	s_barrier
	s_add_i32 s83, s83, 2
	s_add_u32 s68, s68, 0x100
	s_addc_u32 s69, s69, 0
	s_cmp_gt_u32 s83, 13
	s_cbranch_scc0 .LBB0_1135
	s_and_b64 vcc, exec, s[40:41]
	s_cbranch_vccz .LBB0_1138
	s_barrier

.LBB0_1371:
	v_add_u32_e32 v147, s64, v143
	v_add_u32_e32 v152, s64, v144
	ds_read_b128 v[148:151], v147
	ds_read_b128 v[152:155], v152
	v_add_u32_e32 v147, s65, v143
	v_add_u32_e32 v162, s65, v144
	s_add_u32 s58, s18, s56
	ds_read_b128 v[158:161], v147
	ds_read_b128 v[162:165], v162
	v_add_u32_e32 v147, s66, v143
	s_addc_u32 s59, s19, s57
	v_add_u32_e32 v166, s66, v144
	ds_read_b128 v[170:173], v147
	ds_read_b128 v[174:177], v166
	v_add_u32_e32 v147, s67, v143
	s_add_u32 s58, s58, 0x100
	v_add_u32_e32 v166, s67, v144
	ds_read_b128 v[178:181], v147
	ds_read_b128 v[182:185], v166
	s_addc_u32 s59, s59, 0
	s_add_u32 s78, s53, s56
	s_addc_u32 s79, s72, s57
	s_cmpk_eq_i32 s56, 0x1f00
	s_cselect_b32 s79, s49, s79
	s_cselect_b32 s78, s76, s78
	s_cselect_b32 s59, s51, s59
	s_cselect_b32 s58, s73, s58
	v_lshl_add_u64 v[166:167], v[140:141], 0, s[56:57]
	v_lshl_add_u64 v[218:219], v[166:167], 0, s[24:25]
	s_add_i32 m0, s35, 0x8000
	ds_read_b128 v[186:189], v145
	ds_read_b128 v[190:193], v145 offset:2048
	ds_read_b128 v[194:197], v146
	ds_read_b128 v[198:201], v146 offset:2048
	ds_read_b128 v[202:205], v145 offset:4096
	ds_read_b128 v[206:209], v145 offset:6144
	ds_read_b128 v[210:213], v146 offset:4096
	ds_read_b128 v[214:217], v146 offset:6144
	global_load_lds_dwordx4 v[218:219], off
	v_lshl_add_u64 v[218:219], v[166:167], 0, s[44:45]
	s_add_i32 m0, s35, 0xa000
	s_nop 0
	global_load_lds_dwordx4 v[218:219], off
	v_lshl_add_u64 v[218:219], v[166:167], 0, s[28:29]
	s_add_i32 m0, s35, 0xc000
	v_lshl_add_u64 v[166:167], v[166:167], 0, s[46:47]
	global_load_lds_dwordx4 v[218:219], off
	s_add_i32 m0, s35, 0xe000
	s_nop 0
	global_load_lds_dwordx4 v[166:167], off
	s_waitcnt vmcnt(8)
	s_waitcnt lgkmcnt(0)
	s_barrier
	v_mfma_f32_16x16x32_bf16 v[128:131], v[148:151], v[186:189], v[128:131]
	v_mfma_f32_16x16x32_bf16 v[124:127], v[158:161], v[186:189], v[124:127]
	v_mfma_f32_16x16x32_bf16 v[112:115], v[148:151], v[190:193], v[112:115]
	v_mfma_f32_16x16x32_bf16 v[108:111], v[158:161], v[190:193], v[108:111]
	v_mfma_f32_16x16x32_bf16 v[96:99], v[148:151], v[202:205], v[96:99]
	v_mfma_f32_16x16x32_bf16 v[92:95], v[158:161], v[202:205], v[92:95]
	v_mfma_f32_16x16x32_bf16 v[80:83], v[148:151], v[206:209], v[80:83]
	v_mfma_f32_16x16x32_bf16 v[76:79], v[158:161], v[206:209], v[76:79]
	v_mfma_f32_16x16x32_bf16 v[128:131], v[152:155], v[194:197], v[128:131]
	v_mfma_f32_16x16x32_bf16 v[124:127], v[162:165], v[194:197], v[124:127]
	v_mfma_f32_16x16x32_bf16 v[112:115], v[152:155], v[198:201], v[112:115]
	v_mfma_f32_16x16x32_bf16 v[108:111], v[162:165], v[198:201], v[108:111]
	v_mfma_f32_16x16x32_bf16 v[96:99], v[152:155], v[210:213], v[96:99]
	v_mfma_f32_16x16x32_bf16 v[92:95], v[162:165], v[210:213], v[92:95]
	v_mfma_f32_16x16x32_bf16 v[80:83], v[152:155], v[214:217], v[80:83]
	v_mfma_f32_16x16x32_bf16 v[76:79], v[162:165], v[214:217], v[76:79]
	v_mfma_f32_16x16x32_bf16 v[120:123], v[170:173], v[186:189], v[120:123]
	v_mfma_f32_16x16x32_bf16 v[116:119], v[178:181], v[186:189], v[116:119]
	v_mfma_f32_16x16x32_bf16 v[104:107], v[170:173], v[190:193], v[104:107]
	v_mfma_f32_16x16x32_bf16 v[100:103], v[178:181], v[190:193], v[100:103]
	v_mfma_f32_16x16x32_bf16 v[88:91], v[170:173], v[202:205], v[88:91]
	v_mfma_f32_16x16x32_bf16 v[84:87], v[178:181], v[202:205], v[84:87]
	v_mfma_f32_16x16x32_bf16 v[72:75], v[170:173], v[206:209], v[72:75]
	v_mfma_f32_16x16x32_bf16 v[68:71], v[178:181], v[206:209], v[68:71]
	v_mfma_f32_16x16x32_bf16 v[120:123], v[174:177], v[194:197], v[120:123]
	v_mfma_f32_16x16x32_bf16 v[116:119], v[182:185], v[194:197], v[116:119]
	v_mfma_f32_16x16x32_bf16 v[104:107], v[174:177], v[198:201], v[104:107]
	v_mfma_f32_16x16x32_bf16 v[100:103], v[182:185], v[198:201], v[100:103]
	v_mfma_f32_16x16x32_bf16 v[88:91], v[174:177], v[210:213], v[88:91]
	v_mfma_f32_16x16x32_bf16 v[84:87], v[182:185], v[210:213], v[84:87]
	v_mfma_f32_16x16x32_bf16 v[72:75], v[174:177], v[214:217], v[72:75]
	v_mfma_f32_16x16x32_bf16 v[68:71], v[182:185], v[214:217], v[68:71]
	s_barrier
	v_lshl_add_u64 v[166:167], s[78:79], 0, v[132:133]
	s_add_i32 s78, s64, s34
	s_mov_b32 m0, s78
	ds_read_b128 v[186:189], v145 offset:16384
	ds_read_b128 v[190:193], v145 offset:18432
	ds_read_b128 v[194:197], v146 offset:16384
	ds_read_b128 v[198:201], v146 offset:18432
	ds_read_b128 v[202:205], v145 offset:20480
	ds_read_b128 v[206:209], v145 offset:22528
	ds_read_b128 v[210:213], v146 offset:20480
	ds_read_b128 v[214:217], v146 offset:22528
	global_load_lds_dwordx4 v[166:167], off
	v_lshl_add_u64 v[218:219], v[166:167], 0, s[10:11]
	s_add_i32 m0, s78, 0x2000
	s_add_i32 s78, s66, s34
	global_load_lds_dwordx4 v[218:219], off
	v_lshl_add_u64 v[218:219], v[166:167], 0, s[14:15]
	s_mov_b32 m0, s78
	s_nop 0
	global_load_lds_dwordx4 v[218:219], off
	v_lshl_add_u64 v[218:219], v[166:167], 0, s[16:17]
	s_add_i32 m0, s78, 0x2000
	s_nop 0
	global_load_lds_dwordx4 v[218:219], off
	s_waitcnt vmcnt(4)
	s_waitcnt lgkmcnt(0)
	s_barrier
	v_mfma_f32_16x16x32_bf16 v[64:67], v[148:151], v[186:189], v[64:67]
	v_mfma_f32_16x16x32_bf16 v[60:63], v[158:161], v[186:189], v[60:63]
	v_mfma_f32_16x16x32_bf16 v[48:51], v[148:151], v[190:193], v[48:51]
	v_mfma_f32_16x16x32_bf16 v[44:47], v[158:161], v[190:193], v[44:47]
	v_mfma_f32_16x16x32_bf16 v[32:35], v[148:151], v[202:205], v[32:35]
	v_mfma_f32_16x16x32_bf16 v[28:31], v[158:161], v[202:205], v[28:31]
	v_mfma_f32_16x16x32_bf16 v[16:19], v[148:151], v[206:209], v[16:19]
	v_mfma_f32_16x16x32_bf16 v[12:15], v[158:161], v[206:209], v[12:15]
	v_mfma_f32_16x16x32_bf16 v[64:67], v[152:155], v[194:197], v[64:67]
	v_mfma_f32_16x16x32_bf16 v[60:63], v[162:165], v[194:197], v[60:63]
	v_mfma_f32_16x16x32_bf16 v[48:51], v[152:155], v[198:201], v[48:51]
	v_mfma_f32_16x16x32_bf16 v[44:47], v[162:165], v[198:201], v[44:47]
	v_mfma_f32_16x16x32_bf16 v[32:35], v[152:155], v[210:213], v[32:35]
	v_mfma_f32_16x16x32_bf16 v[28:31], v[162:165], v[210:213], v[28:31]
	v_mfma_f32_16x16x32_bf16 v[16:19], v[152:155], v[214:217], v[16:19]
	v_mfma_f32_16x16x32_bf16 v[12:15], v[162:165], v[214:217], v[12:15]
	v_mfma_f32_16x16x32_bf16 v[56:59], v[170:173], v[186:189], v[56:59]
	v_mfma_f32_16x16x32_bf16 v[52:55], v[178:181], v[186:189], v[52:55]
	v_mfma_f32_16x16x32_bf16 v[40:43], v[170:173], v[190:193], v[40:43]
	v_mfma_f32_16x16x32_bf16 v[36:39], v[178:181], v[190:193], v[36:39]
	v_mfma_f32_16x16x32_bf16 v[24:27], v[170:173], v[202:205], v[24:27]
	v_mfma_f32_16x16x32_bf16 v[20:23], v[178:181], v[202:205], v[20:23]
	v_mfma_f32_16x16x32_bf16 v[8:11], v[170:173], v[206:209], v[8:11]
	v_mfma_f32_16x16x32_bf16 v[4:7], v[178:181], v[206:209], v[4:7]
	v_mfma_f32_16x16x32_bf16 v[56:59], v[174:177], v[194:197], v[56:59]
	v_mfma_f32_16x16x32_bf16 v[52:55], v[182:185], v[194:197], v[52:55]
	v_mfma_f32_16x16x32_bf16 v[40:43], v[174:177], v[198:201], v[40:43]
	v_mfma_f32_16x16x32_bf16 v[36:39], v[182:185], v[198:201], v[36:39]
	v_mfma_f32_16x16x32_bf16 v[24:27], v[174:177], v[210:213], v[24:27]
	v_mfma_f32_16x16x32_bf16 v[20:23], v[182:185], v[210:213], v[20:23]
	v_mfma_f32_16x16x32_bf16 v[8:11], v[174:177], v[214:217], v[8:11]
	v_mfma_f32_16x16x32_bf16 v[4:7], v[182:185], v[214:217], v[4:7]
	s_barrier
	v_add_u32_e32 v147, s70, v143
	v_add_u32_e32 v152, s70, v144
	ds_read_b128 v[148:151], v147
	ds_read_b128 v[152:155], v152
	v_add_u32_e32 v147, s68, v143
	v_add_u32_e32 v162, s68, v144
	ds_read_b128 v[158:161], v147
	ds_read_b128 v[162:165], v162
	v_add_u32_e32 v147, s71, v143
	v_add_u32_e32 v169, s71, v144
	ds_read_b128 v[170:173], v147
	ds_read_b128 v[174:177], v169
	v_add_u32_e32 v147, s69, v143
	v_add_u32_e32 v169, s69, v144
	ds_read_b128 v[178:181], v147
	ds_read_b128 v[182:185], v169
	s_mov_b32 m0, s35
	v_lshl_add_u64 v[218:219], s[58:59], 0, v[0:1]
	ds_read_b128 v[186:189], v145 offset:32768
	ds_read_b128 v[190:193], v145 offset:34816
	ds_read_b128 v[194:197], v146 offset:32768
	ds_read_b128 v[198:201], v146 offset:34816
	ds_read_b128 v[202:205], v145 offset:36864
	ds_read_b128 v[206:209], v145 offset:38912
	ds_read_b128 v[210:213], v146 offset:36864
	ds_read_b128 v[214:217], v146 offset:38912
	global_load_lds_dwordx4 v[218:219], off
	v_lshl_add_u64 v[220:221], v[218:219], 0, s[20:21]
	s_mov_b32 m0, s39
	s_nop 0
	global_load_lds_dwordx4 v[220:221], off
	v_lshl_add_u64 v[220:221], v[218:219], 0, s[10:11]
	s_mov_b32 m0, s60
	v_lshl_add_u64 v[218:219], v[218:219], 0, s[22:23]
	global_load_lds_dwordx4 v[220:221], off
	s_mov_b32 m0, s61
	s_nop 0
	global_load_lds_dwordx4 v[218:219], off
	s_waitcnt vmcnt(8)
	s_waitcnt lgkmcnt(0)
	s_barrier
	v_mfma_f32_16x16x32_bf16 v[128:131], v[148:151], v[186:189], v[128:131]
	v_mfma_f32_16x16x32_bf16 v[124:127], v[158:161], v[186:189], v[124:127]
	v_mfma_f32_16x16x32_bf16 v[112:115], v[148:151], v[190:193], v[112:115]
	v_mfma_f32_16x16x32_bf16 v[108:111], v[158:161], v[190:193], v[108:111]
	v_mfma_f32_16x16x32_bf16 v[96:99], v[148:151], v[202:205], v[96:99]
	v_mfma_f32_16x16x32_bf16 v[92:95], v[158:161], v[202:205], v[92:95]
	v_mfma_f32_16x16x32_bf16 v[80:83], v[148:151], v[206:209], v[80:83]
	v_mfma_f32_16x16x32_bf16 v[76:79], v[158:161], v[206:209], v[76:79]
	v_mfma_f32_16x16x32_bf16 v[128:131], v[152:155], v[194:197], v[128:131]
	v_mfma_f32_16x16x32_bf16 v[124:127], v[162:165], v[194:197], v[124:127]
	v_mfma_f32_16x16x32_bf16 v[112:115], v[152:155], v[198:201], v[112:115]
	v_mfma_f32_16x16x32_bf16 v[108:111], v[162:165], v[198:201], v[108:111]
	v_mfma_f32_16x16x32_bf16 v[96:99], v[152:155], v[210:213], v[96:99]
	v_mfma_f32_16x16x32_bf16 v[92:95], v[162:165], v[210:213], v[92:95]
	v_mfma_f32_16x16x32_bf16 v[80:83], v[152:155], v[214:217], v[80:83]
	v_mfma_f32_16x16x32_bf16 v[76:79], v[162:165], v[214:217], v[76:79]
	v_mfma_f32_16x16x32_bf16 v[120:123], v[170:173], v[186:189], v[120:123]
	v_mfma_f32_16x16x32_bf16 v[116:119], v[178:181], v[186:189], v[116:119]
	v_mfma_f32_16x16x32_bf16 v[104:107], v[170:173], v[190:193], v[104:107]
	v_mfma_f32_16x16x32_bf16 v[100:103], v[178:181], v[190:193], v[100:103]
	v_mfma_f32_16x16x32_bf16 v[88:91], v[170:173], v[202:205], v[88:91]
	v_mfma_f32_16x16x32_bf16 v[84:87], v[178:181], v[202:205], v[84:87]
	v_mfma_f32_16x16x32_bf16 v[72:75], v[170:173], v[206:209], v[72:75]
	v_mfma_f32_16x16x32_bf16 v[68:71], v[178:181], v[206:209], v[68:71]
	v_mfma_f32_16x16x32_bf16 v[120:123], v[174:177], v[194:197], v[120:123]
	v_mfma_f32_16x16x32_bf16 v[116:119], v[182:185], v[194:197], v[116:119]
	v_mfma_f32_16x16x32_bf16 v[104:107], v[174:177], v[198:201], v[104:107]
	v_mfma_f32_16x16x32_bf16 v[100:103], v[182:185], v[198:201], v[100:103]
	v_mfma_f32_16x16x32_bf16 v[88:91], v[174:177], v[210:213], v[88:91]
	v_mfma_f32_16x16x32_bf16 v[84:87], v[182:185], v[210:213], v[84:87]
	v_mfma_f32_16x16x32_bf16 v[72:75], v[174:177], v[214:217], v[72:75]
	v_mfma_f32_16x16x32_bf16 v[68:71], v[182:185], v[214:217], v[68:71]
	s_barrier
	s_add_i32 s58, s70, s34
	v_lshl_add_u64 v[218:219], v[166:167], 0, s[24:25]
	s_mov_b32 m0, s58
	ds_read_b128 v[186:189], v145 offset:49152
	ds_read_b128 v[190:193], v145 offset:51200
	ds_read_b128 v[194:197], v146 offset:49152
	ds_read_b128 v[198:201], v146 offset:51200
	ds_read_b128 v[202:205], v145 offset:53248
	ds_read_b128 v[206:209], v145 offset:55296
	ds_read_b128 v[210:213], v146 offset:53248
	ds_read_b128 v[214:217], v146 offset:55296
	global_load_lds_dwordx4 v[218:219], off
	v_lshl_add_u64 v[218:219], v[166:167], 0, s[28:29]
	s_add_i32 m0, s58, 0x2000
	s_add_i32 s58, s71, s34
	global_load_lds_dwordx4 v[218:219], off
	v_lshl_add_u64 v[218:219], v[166:167], 0, s[36:37]
	s_mov_b32 m0, s58
	v_lshl_add_u64 v[166:167], v[166:167], 0, s[40:41]
	global_load_lds_dwordx4 v[218:219], off
	s_add_i32 m0, s58, 0x2000
	s_nop 0
	global_load_lds_dwordx4 v[166:167], off
	s_waitcnt vmcnt(4)
	s_waitcnt lgkmcnt(0)
	s_barrier
	v_mfma_f32_16x16x32_bf16 v[64:67], v[148:151], v[186:189], v[64:67]
	v_mfma_f32_16x16x32_bf16 v[60:63], v[158:161], v[186:189], v[60:63]
	v_mfma_f32_16x16x32_bf16 v[48:51], v[148:151], v[190:193], v[48:51]
	v_mfma_f32_16x16x32_bf16 v[44:47], v[158:161], v[190:193], v[44:47]
	v_mfma_f32_16x16x32_bf16 v[32:35], v[148:151], v[202:205], v[32:35]
	v_mfma_f32_16x16x32_bf16 v[28:31], v[158:161], v[202:205], v[28:31]
	v_mfma_f32_16x16x32_bf16 v[16:19], v[148:151], v[206:209], v[16:19]
	v_mfma_f32_16x16x32_bf16 v[12:15], v[158:161], v[206:209], v[12:15]
	v_mfma_f32_16x16x32_bf16 v[64:67], v[152:155], v[194:197], v[64:67]
	v_mfma_f32_16x16x32_bf16 v[60:63], v[162:165], v[194:197], v[60:63]
	v_mfma_f32_16x16x32_bf16 v[48:51], v[152:155], v[198:201], v[48:51]
	v_mfma_f32_16x16x32_bf16 v[44:47], v[162:165], v[198:201], v[44:47]
	v_mfma_f32_16x16x32_bf16 v[32:35], v[152:155], v[210:213], v[32:35]
	v_mfma_f32_16x16x32_bf16 v[28:31], v[162:165], v[210:213], v[28:31]
	v_mfma_f32_16x16x32_bf16 v[16:19], v[152:155], v[214:217], v[16:19]
	v_mfma_f32_16x16x32_bf16 v[12:15], v[162:165], v[214:217], v[12:15]
	v_mfma_f32_16x16x32_bf16 v[56:59], v[170:173], v[186:189], v[56:59]
	v_mfma_f32_16x16x32_bf16 v[52:55], v[178:181], v[186:189], v[52:55]
	v_mfma_f32_16x16x32_bf16 v[40:43], v[170:173], v[190:193], v[40:43]
	v_mfma_f32_16x16x32_bf16 v[36:39], v[178:181], v[190:193], v[36:39]
	v_mfma_f32_16x16x32_bf16 v[24:27], v[170:173], v[202:205], v[24:27]
	v_mfma_f32_16x16x32_bf16 v[20:23], v[178:181], v[202:205], v[20:23]
	v_mfma_f32_16x16x32_bf16 v[8:11], v[170:173], v[206:209], v[8:11]
	v_mfma_f32_16x16x32_bf16 v[4:7], v[178:181], v[206:209], v[4:7]
	v_mfma_f32_16x16x32_bf16 v[56:59], v[174:177], v[194:197], v[56:59]
	v_mfma_f32_16x16x32_bf16 v[52:55], v[182:185], v[194:197], v[52:55]
	v_mfma_f32_16x16x32_bf16 v[40:43], v[174:177], v[198:201], v[40:43]
	v_mfma_f32_16x16x32_bf16 v[36:39], v[182:185], v[198:201], v[36:39]
	v_mfma_f32_16x16x32_bf16 v[24:27], v[174:177], v[210:213], v[24:27]
	v_mfma_f32_16x16x32_bf16 v[20:23], v[182:185], v[210:213], v[20:23]
	v_mfma_f32_16x16x32_bf16 v[8:11], v[174:177], v[214:217], v[8:11]
	v_mfma_f32_16x16x32_bf16 v[4:7], v[182:185], v[214:217], v[4:7]
	s_barrier
	s_add_i32 s77, s77, 2
	s_add_u32 s56, s56, 0x100
	s_addc_u32 s57, s57, 0
	s_cmp_gt_u32 s77, 61
	s_cbranch_scc0 .LBB0_1371
	s_add_u32 s56, s53, 0xffffff00
	s_addc_u32 s57, s72, -1
	s_andn2_b64 vcc, exec, s[6:7]
	s_cbranch_vccnz .LBB0_1362
	v_mov_b32_e32 v4, 0
	s_mov_b32 s0, s48
	s_mov_b32 s8, s50
	s_mov_b64 s[18:19], s[54:55]
	s_mov_b32 s63, s52
	v_mov_b32_e32 v5, v4
	v_mov_b32_e32 v6, v4
	v_mov_b32_e32 v7, v4
	v_mov_b32_e32 v8, v4
	v_mov_b32_e32 v9, v4
	v_mov_b32_e32 v10, v4
	v_mov_b32_e32 v11, v4
	v_mov_b32_e32 v20, v4
	v_mov_b32_e32 v21, v4
	v_mov_b32_e32 v22, v4
	v_mov_b32_e32 v23, v4
	v_mov_b32_e32 v24, v4
	v_mov_b32_e32 v25, v4
	v_mov_b32_e32 v26, v4
	v_mov_b32_e32 v27, v4
	v_mov_b32_e32 v36, v4
	v_mov_b32_e32 v37, v4
	v_mov_b32_e32 v38, v4
	v_mov_b32_e32 v39, v4
	v_mov_b32_e32 v40, v4
	v_mov_b32_e32 v41, v4
	v_mov_b32_e32 v42, v4
	v_mov_b32_e32 v43, v4
	v_mov_b32_e32 v52, v4
	v_mov_b32_e32 v53, v4
	v_mov_b32_e32 v54, v4
	v_mov_b32_e32 v55, v4
	v_mov_b32_e32 v56, v4
	v_mov_b32_e32 v57, v4
	v_mov_b32_e32 v58, v4
	v_mov_b32_e32 v59, v4
	v_mov_b32_e32 v12, v4
	v_mov_b32_e32 v13, v4
	v_mov_b32_e32 v14, v4
	v_mov_b32_e32 v15, v4
	v_mov_b32_e32 v16, v4
	v_mov_b32_e32 v17, v4
	v_mov_b32_e32 v18, v4
	v_mov_b32_e32 v19, v4
	v_mov_b32_e32 v28, v4
	v_mov_b32_e32 v29, v4
	v_mov_b32_e32 v30, v4
	v_mov_b32_e32 v31, v4
	v_mov_b32_e32 v32, v4
	v_mov_b32_e32 v33, v4
	v_mov_b32_e32 v34, v4
	v_mov_b32_e32 v35, v4
	v_mov_b32_e32 v44, v4
	v_mov_b32_e32 v45, v4
	v_mov_b32_e32 v46, v4
	v_mov_b32_e32 v47, v4
	v_mov_b32_e32 v48, v4
	v_mov_b32_e32 v49, v4
	v_mov_b32_e32 v50, v4
	v_mov_b32_e32 v51, v4
	v_mov_b32_e32 v60, v4
	v_mov_b32_e32 v61, v4
	v_mov_b32_e32 v62, v4
	v_mov_b32_e32 v63, v4
	v_mov_b32_e32 v64, v4
	v_mov_b32_e32 v65, v4
	v_mov_b32_e32 v66, v4
	v_mov_b32_e32 v67, v4
	v_mov_b32_e32 v68, v4
	v_mov_b32_e32 v69, v4
	v_mov_b32_e32 v70, v4
	v_mov_b32_e32 v71, v4
	v_mov_b32_e32 v72, v4
	v_mov_b32_e32 v73, v4
	v_mov_b32_e32 v74, v4
	v_mov_b32_e32 v75, v4
	v_mov_b32_e32 v84, v4
	v_mov_b32_e32 v85, v4
	v_mov_b32_e32 v86, v4
	v_mov_b32_e32 v87, v4
	v_mov_b32_e32 v88, v4
	v_mov_b32_e32 v89, v4
	v_mov_b32_e32 v90, v4
	v_mov_b32_e32 v91, v4
	v_mov_b32_e32 v100, v4
	v_mov_b32_e32 v101, v4
	v_mov_b32_e32 v102, v4
	v_mov_b32_e32 v103, v4
	v_mov_b32_e32 v104, v4
	v_mov_b32_e32 v105, v4
	v_mov_b32_e32 v106, v4
	v_mov_b32_e32 v107, v4
	v_mov_b32_e32 v116, v4
	v_mov_b32_e32 v117, v4
	v_mov_b32_e32 v118, v4
	v_mov_b32_e32 v119, v4
	v_mov_b32_e32 v120, v4
	v_mov_b32_e32 v121, v4
	v_mov_b32_e32 v122, v4
	v_mov_b32_e32 v123, v4
	v_mov_b32_e32 v76, v4
	v_mov_b32_e32 v77, v4
	v_mov_b32_e32 v78, v4
	v_mov_b32_e32 v79, v4
	v_mov_b32_e32 v80, v4
	v_mov_b32_e32 v81, v4
	v_mov_b32_e32 v82, v4
	v_mov_b32_e32 v83, v4
	v_mov_b32_e32 v92, v4
	v_mov_b32_e32 v93, v4
	v_mov_b32_e32 v94, v4
	v_mov_b32_e32 v95, v4
	v_mov_b32_e32 v96, v4
	v_mov_b32_e32 v97, v4
	v_mov_b32_e32 v98, v4
	v_mov_b32_e32 v99, v4
	v_mov_b32_e32 v108, v4
	v_mov_b32_e32 v109, v4
	v_mov_b32_e32 v110, v4
	v_mov_b32_e32 v111, v4
	v_mov_b32_e32 v112, v4
	v_mov_b32_e32 v113, v4
	v_mov_b32_e32 v114, v4
	v_mov_b32_e32 v115, v4
	v_mov_b32_e32 v124, v4
	v_mov_b32_e32 v125, v4
	v_mov_b32_e32 v126, v4
	v_mov_b32_e32 v127, v4
	v_mov_b32_e32 v128, v4
	v_mov_b32_e32 v129, v4
	v_mov_b32_e32 v130, v4
	v_mov_b32_e32 v131, v4
	s_andn2_b64 vcc, exec, s[4:5]
	s_cbranch_vccnz .LBB0_1363
